# GEMM K loops: first iteration written out with SrcC=0; the 128 accumulator-clearing moves per unit dropped
# baseline (speedup 1.0000x reference)
.LBB0_162:
	s_ashr_i32 s15, s14, 31
	s_lshl_b64 s[16:17], s[14:15], 20
	s_add_u32 s16, s29, s16
	s_addc_u32 s17, s30, s17
	s_and_b64 s[18:19], s[0:1], exec
	s_cselect_b32 s15, s17, s23
	s_cselect_b32 s54, s16, s22
	s_ashr_i32 s13, s12, 31
	s_lshl_b64 s[18:19], s[12:13], 22
	s_add_u32 s13, s8, s18
	s_addc_u32 s26, s9, s19
	s_ashr_i32 s18, s14, 3
	s_ashr_i32 s19, s18, 31
	s_lshl_b64 s[18:19], s[18:19], 12
	s_add_u32 s18, s13, s18
	s_addc_u32 s19, s26, s19
	s_and_b64 s[26:27], s[0:1], exec
	s_cselect_b32 s13, s19, s25
	s_cselect_b32 s55, s18, s24
	s_add_u32 s22, s22, 0x80080
	s_addc_u32 s23, s23, 0
	s_add_u32 s56, s24, 0x100
	s_addc_u32 s57, s25, 0
	s_mov_b32 s58, -2
	ds_read_b128 v[152:155], v149
	ds_read_b128 v[156:159], v149 offset:1024
	ds_read_b128 v[160:163], v149 offset:2048
	ds_read_b128 v[164:167], v149 offset:3072
	ds_read_b128 v[168:171], v150
	ds_read_b128 v[172:175], v150 offset:1024
	ds_read_b128 v[176:179], v150 offset:2048
	ds_read_b128 v[180:183], v150 offset:3072
	s_add_u32 s24, s22, 0xfff80080
	s_addc_u32 s25, s23, -1
	s_cmp_eq_u32 s58, 28
	s_cselect_b32 s27, s15, s25
	s_cselect_b32 s26, s54, s24
	s_cselect_b32 s25, s13, s57
	s_cselect_b32 s24, s55, s56
	s_add_u32 s98, s24, s6
	s_addc_u32 s99, s25, s7
	s_add_u32 s100, s26, s6
	s_addc_u32 s101, s27, s7
	s_add_i32 m0, s21, 0xc000
	ds_read_b128 v[184:187], v151
	ds_read_b128 v[188:191], v151 offset:1024
	ds_read_b128 v[192:195], v151 offset:2048
	ds_read_b128 v[196:199], v151 offset:3072
	ds_read_b128 v[200:203], v151 offset:4096
	ds_read_b128 v[204:207], v151 offset:5120
	ds_read_b128 v[208:211], v151 offset:6144
	ds_read_b128 v[212:215], v151 offset:7168
	global_load_lds_dwordx4 v136, s[22:23]
	s_add_i32 m0, s21, 0xe000
	s_nop 0
	global_load_lds_dwordx4 v138, s[22:23]
	s_waitcnt vmcnt(8)
	s_waitcnt lgkmcnt(0)
	s_barrier
	s_setprio 1
	s_waitcnt lgkmcnt(0)
	v_mfma_f32_16x16x32_bf16 v[124:127], v[152:155], v[184:187], 0
	v_mfma_f32_16x16x32_bf16 v[120:123], v[160:163], v[184:187], 0
	v_mfma_f32_16x16x32_bf16 v[116:119], v[152:155], v[192:195], 0
	v_mfma_f32_16x16x32_bf16 v[108:111], v[160:163], v[192:195], 0
	v_mfma_f32_16x16x32_bf16 v[100:103], v[152:155], v[200:203], 0
	v_mfma_f32_16x16x32_bf16 v[92:95], v[160:163], v[200:203], 0
	v_mfma_f32_16x16x32_bf16 v[84:87], v[152:155], v[208:211], 0
	v_mfma_f32_16x16x32_bf16 v[76:79], v[160:163], v[208:211], 0
	v_mfma_f32_16x16x32_bf16 v[124:127], v[156:159], v[188:191], v[124:127]
	v_mfma_f32_16x16x32_bf16 v[120:123], v[164:167], v[188:191], v[120:123]
	v_mfma_f32_16x16x32_bf16 v[116:119], v[156:159], v[196:199], v[116:119]
	v_mfma_f32_16x16x32_bf16 v[108:111], v[164:167], v[196:199], v[108:111]
	v_mfma_f32_16x16x32_bf16 v[100:103], v[156:159], v[204:207], v[100:103]
	v_mfma_f32_16x16x32_bf16 v[92:95], v[164:167], v[204:207], v[92:95]
	v_mfma_f32_16x16x32_bf16 v[84:87], v[156:159], v[212:215], v[84:87]
	v_mfma_f32_16x16x32_bf16 v[76:79], v[164:167], v[212:215], v[76:79]
	s_setprio 0
	s_setprio 1
	v_mfma_f32_16x16x32_bf16 v[112:115], v[168:171], v[184:187], 0
	v_mfma_f32_16x16x32_bf16 v[104:107], v[176:179], v[184:187], 0
	v_mfma_f32_16x16x32_bf16 v[96:99], v[168:171], v[192:195], 0
	v_mfma_f32_16x16x32_bf16 v[88:91], v[176:179], v[192:195], 0
	v_mfma_f32_16x16x32_bf16 v[80:83], v[168:171], v[200:203], 0
	v_mfma_f32_16x16x32_bf16 v[72:75], v[176:179], v[200:203], 0
	v_mfma_f32_16x16x32_bf16 v[68:71], v[168:171], v[208:211], 0
	v_mfma_f32_16x16x32_bf16 v[64:67], v[176:179], v[208:211], 0
	v_mfma_f32_16x16x32_bf16 v[112:115], v[172:175], v[188:191], v[112:115]
	v_mfma_f32_16x16x32_bf16 v[104:107], v[180:183], v[188:191], v[104:107]
	v_mfma_f32_16x16x32_bf16 v[96:99], v[172:175], v[196:199], v[96:99]
	v_mfma_f32_16x16x32_bf16 v[88:91], v[180:183], v[196:199], v[88:91]
	v_mfma_f32_16x16x32_bf16 v[80:83], v[172:175], v[204:207], v[80:83]
	v_mfma_f32_16x16x32_bf16 v[72:75], v[180:183], v[204:207], v[72:75]
	v_mfma_f32_16x16x32_bf16 v[68:71], v[172:175], v[212:215], v[68:71]
	v_mfma_f32_16x16x32_bf16 v[64:67], v[180:183], v[212:215], v[64:67]
	s_setprio 0
	s_barrier
	s_add_i32 s59, s43, s28
	s_mov_b32 m0, s59
	ds_read_b128 v[184:187], v151 offset:16384
	ds_read_b128 v[188:191], v151 offset:17408
	ds_read_b128 v[192:195], v151 offset:18432
	ds_read_b128 v[196:199], v151 offset:19456
	ds_read_b128 v[200:203], v151 offset:20480
	ds_read_b128 v[204:207], v151 offset:21504
	ds_read_b128 v[208:211], v151 offset:22528
	ds_read_b128 v[212:215], v151 offset:23552
	global_load_lds_dwordx4 v130, s[24:25]
	s_add_i32 m0, s59, 0x2000
	s_add_u32 s62, s24, 0x200000
	s_addc_u32 s63, s25, 0
	s_add_i32 s59, s48, s28
	global_load_lds_dwordx4 v134, s[24:25]
	s_mov_b32 m0, s59
	s_nop 0
	global_load_lds_dwordx4 v130, s[62:63]
	s_add_i32 m0, s59, 0x2000
	s_nop 0
	global_load_lds_dwordx4 v134, s[62:63]
	s_mov_b32 m0, s21
	s_nop 0
	global_load_lds_dwordx4 v128, s[26:27]
	s_mov_b32 m0, s31
	s_nop 0
	global_load_lds_dwordx4 v132, s[26:27]
	s_waitcnt vmcnt(8)
	s_waitcnt lgkmcnt(0)
	s_barrier
	s_setprio 1
	s_waitcnt lgkmcnt(0)
	v_mfma_f32_16x16x32_bf16 v[60:63], v[152:155], v[184:187], 0
	v_mfma_f32_16x16x32_bf16 v[56:59], v[160:163], v[184:187], 0
	v_mfma_f32_16x16x32_bf16 v[52:55], v[152:155], v[192:195], 0
	v_mfma_f32_16x16x32_bf16 v[44:47], v[160:163], v[192:195], 0
	v_mfma_f32_16x16x32_bf16 v[36:39], v[152:155], v[200:203], 0
	v_mfma_f32_16x16x32_bf16 v[28:31], v[160:163], v[200:203], 0
	v_mfma_f32_16x16x32_bf16 v[20:23], v[152:155], v[208:211], 0
	v_mfma_f32_16x16x32_bf16 v[12:15], v[160:163], v[208:211], 0
	v_mfma_f32_16x16x32_bf16 v[60:63], v[156:159], v[188:191], v[60:63]
	v_mfma_f32_16x16x32_bf16 v[56:59], v[164:167], v[188:191], v[56:59]
	v_mfma_f32_16x16x32_bf16 v[52:55], v[156:159], v[196:199], v[52:55]
	v_mfma_f32_16x16x32_bf16 v[44:47], v[164:167], v[196:199], v[44:47]
	v_mfma_f32_16x16x32_bf16 v[36:39], v[156:159], v[204:207], v[36:39]
	v_mfma_f32_16x16x32_bf16 v[28:31], v[164:167], v[204:207], v[28:31]
	v_mfma_f32_16x16x32_bf16 v[20:23], v[156:159], v[212:215], v[20:23]
	v_mfma_f32_16x16x32_bf16 v[12:15], v[164:167], v[212:215], v[12:15]
	s_setprio 0
	s_setprio 1
	v_mfma_f32_16x16x32_bf16 v[48:51], v[168:171], v[184:187], 0
	v_mfma_f32_16x16x32_bf16 v[40:43], v[176:179], v[184:187], 0
	v_mfma_f32_16x16x32_bf16 v[32:35], v[168:171], v[192:195], 0
	v_mfma_f32_16x16x32_bf16 v[24:27], v[176:179], v[192:195], 0
	v_mfma_f32_16x16x32_bf16 v[16:19], v[168:171], v[200:203], 0
	v_mfma_f32_16x16x32_bf16 v[8:11], v[176:179], v[200:203], 0
	v_mfma_f32_16x16x32_bf16 v[4:7], v[168:171], v[208:211], 0
	v_mfma_f32_16x16x32_bf16 v[0:3], v[176:179], v[208:211], 0
	v_mfma_f32_16x16x32_bf16 v[48:51], v[172:175], v[188:191], v[48:51]
	v_mfma_f32_16x16x32_bf16 v[40:43], v[180:183], v[188:191], v[40:43]
	v_mfma_f32_16x16x32_bf16 v[32:35], v[172:175], v[196:199], v[32:35]
	v_mfma_f32_16x16x32_bf16 v[24:27], v[180:183], v[196:199], v[24:27]
	v_mfma_f32_16x16x32_bf16 v[16:19], v[172:175], v[204:207], v[16:19]
	v_mfma_f32_16x16x32_bf16 v[8:11], v[180:183], v[204:207], v[8:11]
	v_mfma_f32_16x16x32_bf16 v[4:7], v[172:175], v[212:215], v[4:7]
	v_mfma_f32_16x16x32_bf16 v[0:3], v[180:183], v[212:215], v[0:3]
	s_setprio 0
	s_barrier
	s_add_i32 s59, 0, 0x18000
	s_add_i32 s62, 0, 0x1c000
	v_add_u32_e32 v164, s59, v146
	v_add_u32_e32 v180, s62, v146
	ds_read_b128 v[152:155], v164
	ds_read_b128 v[156:159], v164 offset:1024
	ds_read_b128 v[160:163], v164 offset:2048
	ds_read_b128 v[164:167], v164 offset:3072
	ds_read_b128 v[168:171], v180
	ds_read_b128 v[172:175], v180 offset:1024
	ds_read_b128 v[176:179], v180 offset:2048
	ds_read_b128 v[180:183], v180 offset:3072
	s_add_u32 s26, s26, 0x80000
	s_addc_u32 s27, s27, 0
	s_mov_b32 m0, s34
	ds_read_b128 v[184:187], v151 offset:32768
	ds_read_b128 v[188:191], v151 offset:33792
	ds_read_b128 v[192:195], v151 offset:34816
	ds_read_b128 v[196:199], v151 offset:35840
	ds_read_b128 v[200:203], v151 offset:36864
	ds_read_b128 v[204:207], v151 offset:37888
	ds_read_b128 v[208:211], v151 offset:38912
	ds_read_b128 v[212:215], v151 offset:39936
	global_load_lds_dwordx4 v128, s[26:27]
	s_mov_b32 m0, s35
	s_nop 0
	global_load_lds_dwordx4 v132, s[26:27]
	s_waitcnt vmcnt(8)
	s_waitcnt lgkmcnt(0)
	s_barrier
	s_setprio 1
	s_waitcnt lgkmcnt(0)
	v_mfma_f32_16x16x32_bf16 v[124:127], v[152:155], v[184:187], v[124:127]
	v_mfma_f32_16x16x32_bf16 v[120:123], v[160:163], v[184:187], v[120:123]
	v_mfma_f32_16x16x32_bf16 v[116:119], v[152:155], v[192:195], v[116:119]
	v_mfma_f32_16x16x32_bf16 v[108:111], v[160:163], v[192:195], v[108:111]
	v_mfma_f32_16x16x32_bf16 v[100:103], v[152:155], v[200:203], v[100:103]
	v_mfma_f32_16x16x32_bf16 v[92:95], v[160:163], v[200:203], v[92:95]
	v_mfma_f32_16x16x32_bf16 v[84:87], v[152:155], v[208:211], v[84:87]
	v_mfma_f32_16x16x32_bf16 v[76:79], v[160:163], v[208:211], v[76:79]
	v_mfma_f32_16x16x32_bf16 v[124:127], v[156:159], v[188:191], v[124:127]
	v_mfma_f32_16x16x32_bf16 v[120:123], v[164:167], v[188:191], v[120:123]
	v_mfma_f32_16x16x32_bf16 v[116:119], v[156:159], v[196:199], v[116:119]
	v_mfma_f32_16x16x32_bf16 v[108:111], v[164:167], v[196:199], v[108:111]
	v_mfma_f32_16x16x32_bf16 v[100:103], v[156:159], v[204:207], v[100:103]
	v_mfma_f32_16x16x32_bf16 v[92:95], v[164:167], v[204:207], v[92:95]
	v_mfma_f32_16x16x32_bf16 v[84:87], v[156:159], v[212:215], v[84:87]
	v_mfma_f32_16x16x32_bf16 v[76:79], v[164:167], v[212:215], v[76:79]
	s_setprio 0
	s_setprio 1
	v_mfma_f32_16x16x32_bf16 v[112:115], v[168:171], v[184:187], v[112:115]
	v_mfma_f32_16x16x32_bf16 v[104:107], v[176:179], v[184:187], v[104:107]
	v_mfma_f32_16x16x32_bf16 v[96:99], v[168:171], v[192:195], v[96:99]
	v_mfma_f32_16x16x32_bf16 v[88:91], v[176:179], v[192:195], v[88:91]
	v_mfma_f32_16x16x32_bf16 v[80:83], v[168:171], v[200:203], v[80:83]
	v_mfma_f32_16x16x32_bf16 v[72:75], v[176:179], v[200:203], v[72:75]
	v_mfma_f32_16x16x32_bf16 v[68:71], v[168:171], v[208:211], v[68:71]
	v_mfma_f32_16x16x32_bf16 v[64:67], v[176:179], v[208:211], v[64:67]
	v_mfma_f32_16x16x32_bf16 v[112:115], v[172:175], v[188:191], v[112:115]
	v_mfma_f32_16x16x32_bf16 v[104:107], v[180:183], v[188:191], v[104:107]
	v_mfma_f32_16x16x32_bf16 v[96:99], v[172:175], v[196:199], v[96:99]
	v_mfma_f32_16x16x32_bf16 v[88:91], v[180:183], v[196:199], v[88:91]
	v_mfma_f32_16x16x32_bf16 v[80:83], v[172:175], v[204:207], v[80:83]
	v_mfma_f32_16x16x32_bf16 v[72:75], v[180:183], v[204:207], v[72:75]
	v_mfma_f32_16x16x32_bf16 v[68:71], v[172:175], v[212:215], v[68:71]
	v_mfma_f32_16x16x32_bf16 v[64:67], v[180:183], v[212:215], v[64:67]
	s_setprio 0
	s_barrier
	s_add_i32 s26, s59, s28
	s_mov_b32 m0, s26
	ds_read_b128 v[184:187], v151 offset:49152
	ds_read_b128 v[188:191], v151 offset:50176
	ds_read_b128 v[192:195], v151 offset:51200
	ds_read_b128 v[196:199], v151 offset:52224
	ds_read_b128 v[200:203], v151 offset:53248
	ds_read_b128 v[204:207], v151 offset:54272
	ds_read_b128 v[208:211], v151 offset:55296
	ds_read_b128 v[212:215], v151 offset:56320
	global_load_lds_dwordx4 v130, s[98:99]
	s_add_i32 m0, s26, 0x2000
	s_add_u32 s24, s24, 0x200080
	s_addc_u32 s25, s25, 0
	s_add_i32 s26, s62, s28
	global_load_lds_dwordx4 v134, s[98:99]
	s_mov_b32 m0, s26
	s_nop 0
	global_load_lds_dwordx4 v130, s[24:25]
	s_add_i32 m0, s26, 0x2000
	s_nop 0
	global_load_lds_dwordx4 v134, s[24:25]
	s_mov_b32 m0, s37
	s_nop 0
	global_load_lds_dwordx4 v128, s[100:101]
	s_mov_b32 m0, s38
	s_nop 0
	global_load_lds_dwordx4 v132, s[100:101]
	s_waitcnt vmcnt(8)
	s_waitcnt lgkmcnt(0)
	s_barrier
	s_setprio 1
	s_waitcnt lgkmcnt(0)
	v_mfma_f32_16x16x32_bf16 v[60:63], v[152:155], v[184:187], v[60:63]
	v_mfma_f32_16x16x32_bf16 v[56:59], v[160:163], v[184:187], v[56:59]
	v_mfma_f32_16x16x32_bf16 v[52:55], v[152:155], v[192:195], v[52:55]
	v_mfma_f32_16x16x32_bf16 v[44:47], v[160:163], v[192:195], v[44:47]
	v_mfma_f32_16x16x32_bf16 v[36:39], v[152:155], v[200:203], v[36:39]
	v_mfma_f32_16x16x32_bf16 v[28:31], v[160:163], v[200:203], v[28:31]
	v_mfma_f32_16x16x32_bf16 v[20:23], v[152:155], v[208:211], v[20:23]
	v_mfma_f32_16x16x32_bf16 v[12:15], v[160:163], v[208:211], v[12:15]
	v_mfma_f32_16x16x32_bf16 v[60:63], v[156:159], v[188:191], v[60:63]
	v_mfma_f32_16x16x32_bf16 v[56:59], v[164:167], v[188:191], v[56:59]
	v_mfma_f32_16x16x32_bf16 v[52:55], v[156:159], v[196:199], v[52:55]
	v_mfma_f32_16x16x32_bf16 v[44:47], v[164:167], v[196:199], v[44:47]
	v_mfma_f32_16x16x32_bf16 v[36:39], v[156:159], v[204:207], v[36:39]
	v_mfma_f32_16x16x32_bf16 v[28:31], v[164:167], v[204:207], v[28:31]
	v_mfma_f32_16x16x32_bf16 v[20:23], v[156:159], v[212:215], v[20:23]
	v_mfma_f32_16x16x32_bf16 v[12:15], v[164:167], v[212:215], v[12:15]
	s_setprio 0
	s_setprio 1
	v_mfma_f32_16x16x32_bf16 v[48:51], v[168:171], v[184:187], v[48:51]
	v_mfma_f32_16x16x32_bf16 v[40:43], v[176:179], v[184:187], v[40:43]
	v_mfma_f32_16x16x32_bf16 v[32:35], v[168:171], v[192:195], v[32:35]
	v_mfma_f32_16x16x32_bf16 v[24:27], v[176:179], v[192:195], v[24:27]
	v_mfma_f32_16x16x32_bf16 v[16:19], v[168:171], v[200:203], v[16:19]
	v_mfma_f32_16x16x32_bf16 v[8:11], v[176:179], v[200:203], v[8:11]
	v_mfma_f32_16x16x32_bf16 v[4:7], v[168:171], v[208:211], v[4:7]
	v_mfma_f32_16x16x32_bf16 v[0:3], v[176:179], v[208:211], v[0:3]
	v_mfma_f32_16x16x32_bf16 v[48:51], v[172:175], v[188:191], v[48:51]
	v_mfma_f32_16x16x32_bf16 v[40:43], v[180:183], v[188:191], v[40:43]
	v_mfma_f32_16x16x32_bf16 v[32:35], v[172:175], v[196:199], v[32:35]
	v_mfma_f32_16x16x32_bf16 v[24:27], v[180:183], v[196:199], v[24:27]
	v_mfma_f32_16x16x32_bf16 v[16:19], v[172:175], v[204:207], v[16:19]
	v_mfma_f32_16x16x32_bf16 v[8:11], v[180:183], v[204:207], v[8:11]
	v_mfma_f32_16x16x32_bf16 v[4:7], v[172:175], v[212:215], v[4:7]
	v_mfma_f32_16x16x32_bf16 v[0:3], v[180:183], v[212:215], v[0:3]
	s_setprio 0
	s_barrier
	s_add_i32 s58, s58, 2
	s_add_u32 s22, s22, 0x100
	s_addc_u32 s23, s23, 0
	s_add_u32 s56, s56, 0x100
	s_addc_u32 s57, s57, 0
	s_cmp_gt_u32 s58, 29
	s_cbranch_scc0 .LBB0_163

.Lp2_noswap:
	s_add_u32 s30, s30, 0x100080
	s_addc_u32 s31, s31, 0
	s_add_u32 s75, s34, 0x100
	s_addc_u32 s78, s35, 0
	s_mov_b32 s79, -2
	ds_read_b128 v[154:157], v149
	ds_read_b128 v[158:161], v149 offset:1024
	ds_read_b128 v[162:165], v149 offset:2048
	ds_read_b128 v[166:169], v149 offset:3072
	ds_read_b128 v[170:173], v150
	ds_read_b128 v[174:177], v150 offset:1024
	ds_read_b128 v[178:181], v150 offset:2048
	ds_read_b128 v[182:185], v150 offset:3072
	s_add_u32 s34, s30, 0xfff00080
	s_addc_u32 s35, s31, -1
	s_cmp_eq_u32 s79, 60
	s_cselect_b32 s37, s23, s35
	s_cselect_b32 s36, s73, s34
	s_cselect_b32 s35, s21, s78
	s_cselect_b32 s34, s74, s75
	s_add_u32 s98, s34, s10
	s_addc_u32 s99, s35, s11
	s_add_u32 s100, s36, s10
	s_addc_u32 s101, s37, s11
	s_add_i32 m0, s49, 0xc000
	ds_read_b128 v[186:189], v151
	ds_read_b128 v[190:193], v151 offset:1024
	ds_read_b128 v[194:197], v151 offset:2048
	ds_read_b128 v[198:201], v151 offset:3072
	ds_read_b128 v[202:205], v151 offset:4096
	ds_read_b128 v[206:209], v151 offset:5120
	ds_read_b128 v[210:213], v151 offset:6144
	ds_read_b128 v[214:217], v151 offset:7168
	global_load_lds_dwordx4 v136, s[30:31]
	s_add_i32 m0, s49, 0xe000
	s_nop 0
	global_load_lds_dwordx4 v138, s[30:31]
	s_waitcnt vmcnt(8)
	s_waitcnt lgkmcnt(0)
	s_barrier
	s_setprio 1
	s_waitcnt lgkmcnt(0)
	v_mfma_f32_16x16x32_bf16 v[124:127], v[154:157], v[186:189], 0
	v_mfma_f32_16x16x32_bf16 v[120:123], v[162:165], v[186:189], 0
	v_mfma_f32_16x16x32_bf16 v[116:119], v[154:157], v[194:197], 0
	v_mfma_f32_16x16x32_bf16 v[112:115], v[162:165], v[194:197], 0
	v_mfma_f32_16x16x32_bf16 v[104:107], v[154:157], v[202:205], 0
	v_mfma_f32_16x16x32_bf16 v[96:99], v[162:165], v[202:205], 0
	v_mfma_f32_16x16x32_bf16 v[76:79], v[154:157], v[210:213], 0
	v_mfma_f32_16x16x32_bf16 v[72:75], v[162:165], v[210:213], 0
	v_mfma_f32_16x16x32_bf16 v[124:127], v[158:161], v[190:193], v[124:127]
	v_mfma_f32_16x16x32_bf16 v[120:123], v[166:169], v[190:193], v[120:123]
	v_mfma_f32_16x16x32_bf16 v[116:119], v[158:161], v[198:201], v[116:119]
	v_mfma_f32_16x16x32_bf16 v[112:115], v[166:169], v[198:201], v[112:115]
	v_mfma_f32_16x16x32_bf16 v[104:107], v[158:161], v[206:209], v[104:107]
	v_mfma_f32_16x16x32_bf16 v[96:99], v[166:169], v[206:209], v[96:99]
	v_mfma_f32_16x16x32_bf16 v[76:79], v[158:161], v[214:217], v[76:79]
	v_mfma_f32_16x16x32_bf16 v[72:75], v[166:169], v[214:217], v[72:75]
	s_setprio 0
	s_setprio 1
	v_mfma_f32_16x16x32_bf16 v[108:111], v[170:173], v[186:189], 0
	v_mfma_f32_16x16x32_bf16 v[100:103], v[178:181], v[186:189], 0
	v_mfma_f32_16x16x32_bf16 v[92:95], v[170:173], v[194:197], 0
	v_mfma_f32_16x16x32_bf16 v[88:91], v[178:181], v[194:197], 0
	v_mfma_f32_16x16x32_bf16 v[84:87], v[170:173], v[202:205], 0
	v_mfma_f32_16x16x32_bf16 v[80:83], v[178:181], v[202:205], 0
	v_mfma_f32_16x16x32_bf16 v[68:71], v[170:173], v[210:213], 0
	v_mfma_f32_16x16x32_bf16 v[64:67], v[178:181], v[210:213], 0
	v_mfma_f32_16x16x32_bf16 v[108:111], v[174:177], v[190:193], v[108:111]
	v_mfma_f32_16x16x32_bf16 v[100:103], v[182:185], v[190:193], v[100:103]
	v_mfma_f32_16x16x32_bf16 v[92:95], v[174:177], v[198:201], v[92:95]
	v_mfma_f32_16x16x32_bf16 v[88:91], v[182:185], v[198:201], v[88:91]
	v_mfma_f32_16x16x32_bf16 v[84:87], v[174:177], v[206:209], v[84:87]
	v_mfma_f32_16x16x32_bf16 v[80:83], v[182:185], v[206:209], v[80:83]
	v_mfma_f32_16x16x32_bf16 v[68:71], v[174:177], v[214:217], v[68:71]
	v_mfma_f32_16x16x32_bf16 v[64:67], v[182:185], v[214:217], v[64:67]
	s_setprio 0
	s_barrier
	s_add_i32 s80, s63, s38
	s_mov_b32 m0, s80
	ds_read_b128 v[186:189], v151 offset:16384
	ds_read_b128 v[190:193], v151 offset:17408
	ds_read_b128 v[194:197], v151 offset:18432
	ds_read_b128 v[198:201], v151 offset:19456
	ds_read_b128 v[202:205], v151 offset:20480
	ds_read_b128 v[206:209], v151 offset:21504
	ds_read_b128 v[210:213], v151 offset:22528
	ds_read_b128 v[214:217], v151 offset:23552
	global_load_lds_dwordx4 v130, s[34:35]
	s_add_i32 m0, s80, 0x2000
	s_add_u32 s80, s34, 0x100000
	s_addc_u32 s81, s35, 0
	s_add_i32 s82, s68, s38
	global_load_lds_dwordx4 v134, s[34:35]
	s_mov_b32 m0, s82
	s_nop 0
	global_load_lds_dwordx4 v130, s[80:81]
	s_add_i32 m0, s82, 0x2000
	s_nop 0
	global_load_lds_dwordx4 v134, s[80:81]
	s_mov_b32 m0, s49
	s_nop 0
	global_load_lds_dwordx4 v128, s[36:37]
	s_mov_b32 m0, s54
	s_nop 0
	global_load_lds_dwordx4 v132, s[36:37]
	s_waitcnt vmcnt(8)
	s_waitcnt lgkmcnt(0)
	s_barrier
	s_setprio 1
	s_waitcnt lgkmcnt(0)
	v_mfma_f32_16x16x32_bf16 v[60:63], v[154:157], v[186:189], 0
	v_mfma_f32_16x16x32_bf16 v[56:59], v[162:165], v[186:189], 0
	v_mfma_f32_16x16x32_bf16 v[44:47], v[154:157], v[194:197], 0
	v_mfma_f32_16x16x32_bf16 v[40:43], v[162:165], v[194:197], 0
	v_mfma_f32_16x16x32_bf16 v[28:31], v[154:157], v[202:205], 0
	v_mfma_f32_16x16x32_bf16 v[24:27], v[162:165], v[202:205], 0
	v_mfma_f32_16x16x32_bf16 v[12:15], v[154:157], v[210:213], 0
	v_mfma_f32_16x16x32_bf16 v[8:11], v[162:165], v[210:213], 0
	v_mfma_f32_16x16x32_bf16 v[60:63], v[158:161], v[190:193], v[60:63]
	v_mfma_f32_16x16x32_bf16 v[56:59], v[166:169], v[190:193], v[56:59]
	v_mfma_f32_16x16x32_bf16 v[44:47], v[158:161], v[198:201], v[44:47]
	v_mfma_f32_16x16x32_bf16 v[40:43], v[166:169], v[198:201], v[40:43]
	v_mfma_f32_16x16x32_bf16 v[28:31], v[158:161], v[206:209], v[28:31]
	v_mfma_f32_16x16x32_bf16 v[24:27], v[166:169], v[206:209], v[24:27]
	v_mfma_f32_16x16x32_bf16 v[12:15], v[158:161], v[214:217], v[12:15]
	v_mfma_f32_16x16x32_bf16 v[8:11], v[166:169], v[214:217], v[8:11]
	s_setprio 0
	s_setprio 1
	v_mfma_f32_16x16x32_bf16 v[52:55], v[170:173], v[186:189], 0
	v_mfma_f32_16x16x32_bf16 v[48:51], v[178:181], v[186:189], 0
	v_mfma_f32_16x16x32_bf16 v[36:39], v[170:173], v[194:197], 0
	v_mfma_f32_16x16x32_bf16 v[32:35], v[178:181], v[194:197], 0
	v_mfma_f32_16x16x32_bf16 v[20:23], v[170:173], v[202:205], 0
	v_mfma_f32_16x16x32_bf16 v[16:19], v[178:181], v[202:205], 0
	v_mfma_f32_16x16x32_bf16 v[4:7], v[170:173], v[210:213], 0
	v_mfma_f32_16x16x32_bf16 v[0:3], v[178:181], v[210:213], 0
	v_mfma_f32_16x16x32_bf16 v[52:55], v[174:177], v[190:193], v[52:55]
	v_mfma_f32_16x16x32_bf16 v[48:51], v[182:185], v[190:193], v[48:51]
	v_mfma_f32_16x16x32_bf16 v[36:39], v[174:177], v[198:201], v[36:39]
	v_mfma_f32_16x16x32_bf16 v[32:35], v[182:185], v[198:201], v[32:35]
	v_mfma_f32_16x16x32_bf16 v[20:23], v[174:177], v[206:209], v[20:23]
	v_mfma_f32_16x16x32_bf16 v[16:19], v[182:185], v[206:209], v[16:19]
	v_mfma_f32_16x16x32_bf16 v[4:7], v[174:177], v[214:217], v[4:7]
	v_mfma_f32_16x16x32_bf16 v[0:3], v[182:185], v[214:217], v[0:3]
	s_setprio 0
	s_barrier
	s_add_i32 s80, 0, 0x18000
	s_add_i32 s81, 0, 0x1c000
	v_add_u32_e32 v166, s80, v147
	v_add_u32_e32 v182, s81, v147
	ds_read_b128 v[154:157], v166
	ds_read_b128 v[158:161], v166 offset:1024
	ds_read_b128 v[162:165], v166 offset:2048
	ds_read_b128 v[166:169], v166 offset:3072
	ds_read_b128 v[170:173], v182
	ds_read_b128 v[174:177], v182 offset:1024
	ds_read_b128 v[178:181], v182 offset:2048
	ds_read_b128 v[182:185], v182 offset:3072
	s_add_u32 s36, s36, 0x100000
	s_addc_u32 s37, s37, 0
	s_mov_b32 m0, s55
	ds_read_b128 v[186:189], v151 offset:32768
	ds_read_b128 v[190:193], v151 offset:33792
	ds_read_b128 v[194:197], v151 offset:34816
	ds_read_b128 v[198:201], v151 offset:35840
	ds_read_b128 v[202:205], v151 offset:36864
	ds_read_b128 v[206:209], v151 offset:37888
	ds_read_b128 v[210:213], v151 offset:38912
	ds_read_b128 v[214:217], v151 offset:39936
	global_load_lds_dwordx4 v128, s[36:37]
	s_mov_b32 m0, s56
	s_nop 0
	global_load_lds_dwordx4 v132, s[36:37]
	s_waitcnt vmcnt(8)
	s_waitcnt lgkmcnt(0)
	s_barrier
	s_setprio 1
	s_waitcnt lgkmcnt(0)
	v_mfma_f32_16x16x32_bf16 v[124:127], v[154:157], v[186:189], v[124:127]
	v_mfma_f32_16x16x32_bf16 v[120:123], v[162:165], v[186:189], v[120:123]
	v_mfma_f32_16x16x32_bf16 v[116:119], v[154:157], v[194:197], v[116:119]
	v_mfma_f32_16x16x32_bf16 v[112:115], v[162:165], v[194:197], v[112:115]
	v_mfma_f32_16x16x32_bf16 v[104:107], v[154:157], v[202:205], v[104:107]
	v_mfma_f32_16x16x32_bf16 v[96:99], v[162:165], v[202:205], v[96:99]
	v_mfma_f32_16x16x32_bf16 v[76:79], v[154:157], v[210:213], v[76:79]
	v_mfma_f32_16x16x32_bf16 v[72:75], v[162:165], v[210:213], v[72:75]
	v_mfma_f32_16x16x32_bf16 v[124:127], v[158:161], v[190:193], v[124:127]
	v_mfma_f32_16x16x32_bf16 v[120:123], v[166:169], v[190:193], v[120:123]
	v_mfma_f32_16x16x32_bf16 v[116:119], v[158:161], v[198:201], v[116:119]
	v_mfma_f32_16x16x32_bf16 v[112:115], v[166:169], v[198:201], v[112:115]
	v_mfma_f32_16x16x32_bf16 v[104:107], v[158:161], v[206:209], v[104:107]
	v_mfma_f32_16x16x32_bf16 v[96:99], v[166:169], v[206:209], v[96:99]
	v_mfma_f32_16x16x32_bf16 v[76:79], v[158:161], v[214:217], v[76:79]
	v_mfma_f32_16x16x32_bf16 v[72:75], v[166:169], v[214:217], v[72:75]
	s_setprio 0
	s_setprio 1
	v_mfma_f32_16x16x32_bf16 v[108:111], v[170:173], v[186:189], v[108:111]
	v_mfma_f32_16x16x32_bf16 v[100:103], v[178:181], v[186:189], v[100:103]
	v_mfma_f32_16x16x32_bf16 v[92:95], v[170:173], v[194:197], v[92:95]
	v_mfma_f32_16x16x32_bf16 v[88:91], v[178:181], v[194:197], v[88:91]
	v_mfma_f32_16x16x32_bf16 v[84:87], v[170:173], v[202:205], v[84:87]
	v_mfma_f32_16x16x32_bf16 v[80:83], v[178:181], v[202:205], v[80:83]
	v_mfma_f32_16x16x32_bf16 v[68:71], v[170:173], v[210:213], v[68:71]
	v_mfma_f32_16x16x32_bf16 v[64:67], v[178:181], v[210:213], v[64:67]
	v_mfma_f32_16x16x32_bf16 v[108:111], v[174:177], v[190:193], v[108:111]
	v_mfma_f32_16x16x32_bf16 v[100:103], v[182:185], v[190:193], v[100:103]
	v_mfma_f32_16x16x32_bf16 v[92:95], v[174:177], v[198:201], v[92:95]
	v_mfma_f32_16x16x32_bf16 v[88:91], v[182:185], v[198:201], v[88:91]
	v_mfma_f32_16x16x32_bf16 v[84:87], v[174:177], v[206:209], v[84:87]
	v_mfma_f32_16x16x32_bf16 v[80:83], v[182:185], v[206:209], v[80:83]
	v_mfma_f32_16x16x32_bf16 v[68:71], v[174:177], v[214:217], v[68:71]
	v_mfma_f32_16x16x32_bf16 v[64:67], v[182:185], v[214:217], v[64:67]
	s_setprio 0
	s_barrier
	s_add_i32 s36, s80, s38
	s_mov_b32 m0, s36
	ds_read_b128 v[186:189], v151 offset:49152
	ds_read_b128 v[190:193], v151 offset:50176
	ds_read_b128 v[194:197], v151 offset:51200
	ds_read_b128 v[198:201], v151 offset:52224
	ds_read_b128 v[202:205], v151 offset:53248
	ds_read_b128 v[206:209], v151 offset:54272
	ds_read_b128 v[210:213], v151 offset:55296
	ds_read_b128 v[214:217], v151 offset:56320
	global_load_lds_dwordx4 v130, s[98:99]
	s_add_i32 m0, s36, 0x2000
	s_add_u32 s34, s34, 0x100080
	s_addc_u32 s35, s35, 0
	s_add_i32 s36, s81, s38
	global_load_lds_dwordx4 v134, s[98:99]
	s_mov_b32 m0, s36
	s_nop 0
	global_load_lds_dwordx4 v130, s[34:35]
	s_add_i32 m0, s36, 0x2000
	s_nop 0
	global_load_lds_dwordx4 v134, s[34:35]
	s_mov_b32 m0, s58
	s_nop 0
	global_load_lds_dwordx4 v128, s[100:101]
	s_mov_b32 m0, s59
	s_nop 0
	global_load_lds_dwordx4 v132, s[100:101]
	s_waitcnt vmcnt(8)
	s_waitcnt lgkmcnt(0)
	s_barrier
	s_setprio 1
	s_waitcnt lgkmcnt(0)
	v_mfma_f32_16x16x32_bf16 v[60:63], v[154:157], v[186:189], v[60:63]
	v_mfma_f32_16x16x32_bf16 v[56:59], v[162:165], v[186:189], v[56:59]
	v_mfma_f32_16x16x32_bf16 v[44:47], v[154:157], v[194:197], v[44:47]
	v_mfma_f32_16x16x32_bf16 v[40:43], v[162:165], v[194:197], v[40:43]
	v_mfma_f32_16x16x32_bf16 v[28:31], v[154:157], v[202:205], v[28:31]
	v_mfma_f32_16x16x32_bf16 v[24:27], v[162:165], v[202:205], v[24:27]
	v_mfma_f32_16x16x32_bf16 v[12:15], v[154:157], v[210:213], v[12:15]
	v_mfma_f32_16x16x32_bf16 v[8:11], v[162:165], v[210:213], v[8:11]
	v_mfma_f32_16x16x32_bf16 v[60:63], v[158:161], v[190:193], v[60:63]
	v_mfma_f32_16x16x32_bf16 v[56:59], v[166:169], v[190:193], v[56:59]
	v_mfma_f32_16x16x32_bf16 v[44:47], v[158:161], v[198:201], v[44:47]
	v_mfma_f32_16x16x32_bf16 v[40:43], v[166:169], v[198:201], v[40:43]
	v_mfma_f32_16x16x32_bf16 v[28:31], v[158:161], v[206:209], v[28:31]
	v_mfma_f32_16x16x32_bf16 v[24:27], v[166:169], v[206:209], v[24:27]
	v_mfma_f32_16x16x32_bf16 v[12:15], v[158:161], v[214:217], v[12:15]
	v_mfma_f32_16x16x32_bf16 v[8:11], v[166:169], v[214:217], v[8:11]
	s_setprio 0
	s_setprio 1
	v_mfma_f32_16x16x32_bf16 v[52:55], v[170:173], v[186:189], v[52:55]
	v_mfma_f32_16x16x32_bf16 v[48:51], v[178:181], v[186:189], v[48:51]
	v_mfma_f32_16x16x32_bf16 v[36:39], v[170:173], v[194:197], v[36:39]
	v_mfma_f32_16x16x32_bf16 v[32:35], v[178:181], v[194:197], v[32:35]
	v_mfma_f32_16x16x32_bf16 v[20:23], v[170:173], v[202:205], v[20:23]
	v_mfma_f32_16x16x32_bf16 v[16:19], v[178:181], v[202:205], v[16:19]
	v_mfma_f32_16x16x32_bf16 v[4:7], v[170:173], v[210:213], v[4:7]
	v_mfma_f32_16x16x32_bf16 v[0:3], v[178:181], v[210:213], v[0:3]
	v_mfma_f32_16x16x32_bf16 v[52:55], v[174:177], v[190:193], v[52:55]
	v_mfma_f32_16x16x32_bf16 v[48:51], v[182:185], v[190:193], v[48:51]
	v_mfma_f32_16x16x32_bf16 v[36:39], v[174:177], v[198:201], v[36:39]
	v_mfma_f32_16x16x32_bf16 v[32:35], v[182:185], v[198:201], v[32:35]
	v_mfma_f32_16x16x32_bf16 v[20:23], v[174:177], v[206:209], v[20:23]
	v_mfma_f32_16x16x32_bf16 v[16:19], v[182:185], v[206:209], v[16:19]
	v_mfma_f32_16x16x32_bf16 v[4:7], v[174:177], v[214:217], v[4:7]
	v_mfma_f32_16x16x32_bf16 v[0:3], v[182:185], v[214:217], v[0:3]
	s_setprio 0
	s_barrier
	s_add_i32 s79, s79, 2
	s_add_u32 s30, s30, 0x100
	s_addc_u32 s31, s31, 0
	s_add_u32 s75, s75, 0x100
	s_addc_u32 s78, s78, 0
	s_cmp_gt_u32 s79, 61
	s_cbranch_scc0 .LBB0_188

.LBB0_430:
	s_ashr_i32 s15, s14, 31
	s_lshl_b64 s[16:17], s[14:15], 21
	s_add_u32 s16, s56, s16
	s_addc_u32 s17, s57, s17
	s_and_b64 s[18:19], s[4:5], exec
	s_cselect_b32 s15, s17, s27
	s_cselect_b32 s21, s16, s26
	s_ashr_i32 s13, s12, 31
	s_lshl_b64 s[18:19], s[12:13], 21
	v_readlane_b32 s30, v254, 5
	v_readlane_b32 s31, v254, 6
	s_add_u32 s18, s30, s18
	s_addc_u32 s19, s31, s19
	s_and_b64 s[30:31], s[4:5], exec
	s_cselect_b32 s13, s19, s29
	s_cselect_b32 s52, s18, s28
	s_add_u32 s26, s26, 0x100080
	s_addc_u32 s27, s27, 0
	s_add_u32 s53, s28, 0x100
	s_addc_u32 s54, s29, 0
	s_mov_b32 s55, -2
	s_waitcnt lgkmcnt(0)
	ds_read_b128 v[128:131], v207
	ds_read_b128 v[132:135], v207 offset:1024
	ds_read_b128 v[136:139], v207 offset:2048
	ds_read_b128 v[140:143], v207 offset:3072
	ds_read_b128 v[144:147], v208
	ds_read_b128 v[148:151], v208 offset:1024
	ds_read_b128 v[152:155], v208 offset:2048
	ds_read_b128 v[156:159], v208 offset:3072
	s_add_u32 s28, s26, 0xfff00080
	s_addc_u32 s29, s27, -1
	s_cmp_eq_u32 s55, 60
	s_cselect_b32 s31, s15, s29
	s_cselect_b32 s30, s21, s28
	s_cselect_b32 s29, s13, s54
	s_cselect_b32 s28, s52, s53
	s_add_u32 s98, s28, s8
	s_addc_u32 s99, s29, s9
	s_add_u32 s100, s30, s8
	s_addc_u32 s101, s31, s9
	s_add_i32 m0, s23, 0xc000
	ds_read_b128 v[160:163], v209
	ds_read_b128 v[164:167], v209 offset:1024
	ds_read_b128 v[168:171], v209 offset:2048
	ds_read_b128 v[172:175], v209 offset:3072
	ds_read_b128 v[192:195], v209 offset:4096
	ds_read_b128 v[196:199], v209 offset:5120
	ds_read_b128 v[200:203], v209 offset:6144
	ds_read_b128 v[212:215], v209 offset:7168
	global_load_lds_dwordx4 v184, s[26:27]
	s_add_i32 m0, s23, 0xe000
	s_nop 0
	global_load_lds_dwordx4 v186, s[26:27]
	s_waitcnt vmcnt(8)
	s_waitcnt lgkmcnt(0)
	s_barrier
	s_setprio 1
	s_waitcnt lgkmcnt(0)
	v_mfma_f32_16x16x32_bf16 v[124:127], v[128:131], v[160:163], 0
	v_mfma_f32_16x16x32_bf16 v[120:123], v[136:139], v[160:163], 0
	v_mfma_f32_16x16x32_bf16 v[108:111], v[128:131], v[168:171], 0
	v_mfma_f32_16x16x32_bf16 v[104:107], v[136:139], v[168:171], 0
	v_mfma_f32_16x16x32_bf16 v[92:95], v[128:131], v[192:195], 0
	v_mfma_f32_16x16x32_bf16 v[88:91], v[136:139], v[192:195], 0
	v_mfma_f32_16x16x32_bf16 v[76:79], v[128:131], v[200:203], 0
	v_mfma_f32_16x16x32_bf16 v[72:75], v[136:139], v[200:203], 0
	v_mfma_f32_16x16x32_bf16 v[124:127], v[132:135], v[164:167], v[124:127]
	v_mfma_f32_16x16x32_bf16 v[120:123], v[140:143], v[164:167], v[120:123]
	v_mfma_f32_16x16x32_bf16 v[108:111], v[132:135], v[172:175], v[108:111]
	v_mfma_f32_16x16x32_bf16 v[104:107], v[140:143], v[172:175], v[104:107]
	v_mfma_f32_16x16x32_bf16 v[92:95], v[132:135], v[196:199], v[92:95]
	v_mfma_f32_16x16x32_bf16 v[88:91], v[140:143], v[196:199], v[88:91]
	v_mfma_f32_16x16x32_bf16 v[76:79], v[132:135], v[212:215], v[76:79]
	v_mfma_f32_16x16x32_bf16 v[72:75], v[140:143], v[212:215], v[72:75]
	s_setprio 0
	s_setprio 1
	v_mfma_f32_16x16x32_bf16 v[116:119], v[144:147], v[160:163], 0
	v_mfma_f32_16x16x32_bf16 v[112:115], v[152:155], v[160:163], 0
	v_mfma_f32_16x16x32_bf16 v[100:103], v[144:147], v[168:171], 0
	v_mfma_f32_16x16x32_bf16 v[96:99], v[152:155], v[168:171], 0
	v_mfma_f32_16x16x32_bf16 v[84:87], v[144:147], v[192:195], 0
	v_mfma_f32_16x16x32_bf16 v[80:83], v[152:155], v[192:195], 0
	v_mfma_f32_16x16x32_bf16 v[68:71], v[144:147], v[200:203], 0
	v_mfma_f32_16x16x32_bf16 v[64:67], v[152:155], v[200:203], 0
	v_mfma_f32_16x16x32_bf16 v[116:119], v[148:151], v[164:167], v[116:119]
	v_mfma_f32_16x16x32_bf16 v[112:115], v[156:159], v[164:167], v[112:115]
	v_mfma_f32_16x16x32_bf16 v[100:103], v[148:151], v[172:175], v[100:103]
	v_mfma_f32_16x16x32_bf16 v[96:99], v[156:159], v[172:175], v[96:99]
	v_mfma_f32_16x16x32_bf16 v[84:87], v[148:151], v[196:199], v[84:87]
	v_mfma_f32_16x16x32_bf16 v[80:83], v[156:159], v[196:199], v[80:83]
	v_mfma_f32_16x16x32_bf16 v[68:71], v[148:151], v[212:215], v[68:71]
	v_mfma_f32_16x16x32_bf16 v[64:67], v[156:159], v[212:215], v[64:67]
	s_setprio 0
	s_barrier
	s_add_i32 s58, s50, s3
	s_mov_b32 m0, s58
	ds_read_b128 v[160:163], v209 offset:16384
	ds_read_b128 v[164:167], v209 offset:17408
	ds_read_b128 v[168:171], v209 offset:18432
	ds_read_b128 v[172:175], v209 offset:19456
	ds_read_b128 v[192:195], v209 offset:20480
	ds_read_b128 v[196:199], v209 offset:21504
	ds_read_b128 v[200:203], v209 offset:22528
	ds_read_b128 v[212:215], v209 offset:23552
	global_load_lds_dwordx4 v178, s[28:29]
	s_add_i32 m0, s58, 0x2000
	s_add_u32 s58, s28, 0x100000
	s_addc_u32 s59, s29, 0
	s_add_i32 s62, s51, s3
	global_load_lds_dwordx4 v182, s[28:29]
	s_mov_b32 m0, s62
	s_nop 0
	global_load_lds_dwordx4 v178, s[58:59]
	s_add_i32 m0, s62, 0x2000
	s_nop 0
	global_load_lds_dwordx4 v182, s[58:59]
	s_mov_b32 m0, s23
	s_nop 0
	global_load_lds_dwordx4 v176, s[30:31]
	s_mov_b32 m0, s34
	s_nop 0
	global_load_lds_dwordx4 v180, s[30:31]
	s_waitcnt vmcnt(8)
	s_waitcnt lgkmcnt(0)
	s_barrier
	s_setprio 1
	s_waitcnt lgkmcnt(0)
	v_mfma_f32_16x16x32_bf16 v[60:63], v[128:131], v[160:163], 0
	v_mfma_f32_16x16x32_bf16 v[56:59], v[136:139], v[160:163], 0
	v_mfma_f32_16x16x32_bf16 v[44:47], v[128:131], v[168:171], 0
	v_mfma_f32_16x16x32_bf16 v[40:43], v[136:139], v[168:171], 0
	v_mfma_f32_16x16x32_bf16 v[28:31], v[128:131], v[192:195], 0
	v_mfma_f32_16x16x32_bf16 v[24:27], v[136:139], v[192:195], 0
	v_mfma_f32_16x16x32_bf16 v[12:15], v[128:131], v[200:203], 0
	v_mfma_f32_16x16x32_bf16 v[8:11], v[136:139], v[200:203], 0
	v_mfma_f32_16x16x32_bf16 v[60:63], v[132:135], v[164:167], v[60:63]
	v_mfma_f32_16x16x32_bf16 v[56:59], v[140:143], v[164:167], v[56:59]
	v_mfma_f32_16x16x32_bf16 v[44:47], v[132:135], v[172:175], v[44:47]
	v_mfma_f32_16x16x32_bf16 v[40:43], v[140:143], v[172:175], v[40:43]
	v_mfma_f32_16x16x32_bf16 v[28:31], v[132:135], v[196:199], v[28:31]
	v_mfma_f32_16x16x32_bf16 v[24:27], v[140:143], v[196:199], v[24:27]
	v_mfma_f32_16x16x32_bf16 v[12:15], v[132:135], v[212:215], v[12:15]
	v_mfma_f32_16x16x32_bf16 v[8:11], v[140:143], v[212:215], v[8:11]
	s_setprio 0
	s_setprio 1
	v_mfma_f32_16x16x32_bf16 v[52:55], v[144:147], v[160:163], 0
	v_mfma_f32_16x16x32_bf16 v[48:51], v[152:155], v[160:163], 0
	v_mfma_f32_16x16x32_bf16 v[36:39], v[144:147], v[168:171], 0
	v_mfma_f32_16x16x32_bf16 v[32:35], v[152:155], v[168:171], 0
	v_mfma_f32_16x16x32_bf16 v[20:23], v[144:147], v[192:195], 0
	v_mfma_f32_16x16x32_bf16 v[16:19], v[152:155], v[192:195], 0
	v_mfma_f32_16x16x32_bf16 v[4:7], v[144:147], v[200:203], 0
	v_mfma_f32_16x16x32_bf16 v[0:3], v[152:155], v[200:203], 0
	v_mfma_f32_16x16x32_bf16 v[52:55], v[148:151], v[164:167], v[52:55]
	v_mfma_f32_16x16x32_bf16 v[48:51], v[156:159], v[164:167], v[48:51]
	v_mfma_f32_16x16x32_bf16 v[36:39], v[148:151], v[172:175], v[36:39]
	v_mfma_f32_16x16x32_bf16 v[32:35], v[156:159], v[172:175], v[32:35]
	v_mfma_f32_16x16x32_bf16 v[20:23], v[148:151], v[196:199], v[20:23]
	v_mfma_f32_16x16x32_bf16 v[16:19], v[156:159], v[196:199], v[16:19]
	v_mfma_f32_16x16x32_bf16 v[4:7], v[148:151], v[212:215], v[4:7]
	v_mfma_f32_16x16x32_bf16 v[0:3], v[156:159], v[212:215], v[0:3]
	s_setprio 0
	s_barrier
	s_add_i32 s58, 0, 0x18000
	s_add_i32 s59, 0, 0x1c000
	v_add_u32_e32 v140, s58, v205
	v_add_u32_e32 v156, s59, v205
	ds_read_b128 v[128:131], v140
	ds_read_b128 v[132:135], v140 offset:1024
	ds_read_b128 v[136:139], v140 offset:2048
	ds_read_b128 v[140:143], v140 offset:3072
	ds_read_b128 v[144:147], v156
	ds_read_b128 v[148:151], v156 offset:1024
	ds_read_b128 v[152:155], v156 offset:2048
	ds_read_b128 v[156:159], v156 offset:3072
	s_add_u32 s30, s30, 0x100000
	s_addc_u32 s31, s31, 0
	s_mov_b32 m0, s35
	ds_read_b128 v[160:163], v209 offset:32768
	ds_read_b128 v[164:167], v209 offset:33792
	ds_read_b128 v[168:171], v209 offset:34816
	ds_read_b128 v[172:175], v209 offset:35840
	ds_read_b128 v[192:195], v209 offset:36864
	ds_read_b128 v[196:199], v209 offset:37888
	ds_read_b128 v[200:203], v209 offset:38912
	ds_read_b128 v[212:215], v209 offset:39936
	global_load_lds_dwordx4 v176, s[30:31]
	s_mov_b32 m0, s36
	s_nop 0
	global_load_lds_dwordx4 v180, s[30:31]
	s_waitcnt vmcnt(8)
	s_waitcnt lgkmcnt(0)
	s_barrier
	s_setprio 1
	s_waitcnt lgkmcnt(0)
	v_mfma_f32_16x16x32_bf16 v[124:127], v[128:131], v[160:163], v[124:127]
	v_mfma_f32_16x16x32_bf16 v[120:123], v[136:139], v[160:163], v[120:123]
	v_mfma_f32_16x16x32_bf16 v[108:111], v[128:131], v[168:171], v[108:111]
	v_mfma_f32_16x16x32_bf16 v[104:107], v[136:139], v[168:171], v[104:107]
	v_mfma_f32_16x16x32_bf16 v[92:95], v[128:131], v[192:195], v[92:95]
	v_mfma_f32_16x16x32_bf16 v[88:91], v[136:139], v[192:195], v[88:91]
	v_mfma_f32_16x16x32_bf16 v[76:79], v[128:131], v[200:203], v[76:79]
	v_mfma_f32_16x16x32_bf16 v[72:75], v[136:139], v[200:203], v[72:75]
	v_mfma_f32_16x16x32_bf16 v[124:127], v[132:135], v[164:167], v[124:127]
	v_mfma_f32_16x16x32_bf16 v[120:123], v[140:143], v[164:167], v[120:123]
	v_mfma_f32_16x16x32_bf16 v[108:111], v[132:135], v[172:175], v[108:111]
	v_mfma_f32_16x16x32_bf16 v[104:107], v[140:143], v[172:175], v[104:107]
	v_mfma_f32_16x16x32_bf16 v[92:95], v[132:135], v[196:199], v[92:95]
	v_mfma_f32_16x16x32_bf16 v[88:91], v[140:143], v[196:199], v[88:91]
	v_mfma_f32_16x16x32_bf16 v[76:79], v[132:135], v[212:215], v[76:79]
	v_mfma_f32_16x16x32_bf16 v[72:75], v[140:143], v[212:215], v[72:75]
	s_setprio 0
	s_setprio 1
	v_mfma_f32_16x16x32_bf16 v[116:119], v[144:147], v[160:163], v[116:119]
	v_mfma_f32_16x16x32_bf16 v[112:115], v[152:155], v[160:163], v[112:115]
	v_mfma_f32_16x16x32_bf16 v[100:103], v[144:147], v[168:171], v[100:103]
	v_mfma_f32_16x16x32_bf16 v[96:99], v[152:155], v[168:171], v[96:99]
	v_mfma_f32_16x16x32_bf16 v[84:87], v[144:147], v[192:195], v[84:87]
	v_mfma_f32_16x16x32_bf16 v[80:83], v[152:155], v[192:195], v[80:83]
	v_mfma_f32_16x16x32_bf16 v[68:71], v[144:147], v[200:203], v[68:71]
	v_mfma_f32_16x16x32_bf16 v[64:67], v[152:155], v[200:203], v[64:67]
	v_mfma_f32_16x16x32_bf16 v[116:119], v[148:151], v[164:167], v[116:119]
	v_mfma_f32_16x16x32_bf16 v[112:115], v[156:159], v[164:167], v[112:115]
	v_mfma_f32_16x16x32_bf16 v[100:103], v[148:151], v[172:175], v[100:103]
	v_mfma_f32_16x16x32_bf16 v[96:99], v[156:159], v[172:175], v[96:99]
	v_mfma_f32_16x16x32_bf16 v[84:87], v[148:151], v[196:199], v[84:87]
	v_mfma_f32_16x16x32_bf16 v[80:83], v[156:159], v[196:199], v[80:83]
	v_mfma_f32_16x16x32_bf16 v[68:71], v[148:151], v[212:215], v[68:71]
	v_mfma_f32_16x16x32_bf16 v[64:67], v[156:159], v[212:215], v[64:67]
	s_setprio 0
	s_barrier
	s_add_i32 s30, s58, s3
	s_mov_b32 m0, s30
	ds_read_b128 v[160:163], v209 offset:49152
	ds_read_b128 v[164:167], v209 offset:50176
	ds_read_b128 v[168:171], v209 offset:51200
	ds_read_b128 v[172:175], v209 offset:52224
	ds_read_b128 v[192:195], v209 offset:53248
	ds_read_b128 v[196:199], v209 offset:54272
	ds_read_b128 v[200:203], v209 offset:55296
	ds_read_b128 v[212:215], v209 offset:56320
	global_load_lds_dwordx4 v178, s[98:99]
	s_add_i32 m0, s30, 0x2000
	s_add_u32 s28, s28, 0x100080
	s_addc_u32 s29, s29, 0
	s_add_i32 s30, s59, s3
	global_load_lds_dwordx4 v182, s[98:99]
	s_mov_b32 m0, s30
	s_nop 0
	global_load_lds_dwordx4 v178, s[28:29]
	s_add_i32 m0, s30, 0x2000
	s_nop 0
	global_load_lds_dwordx4 v182, s[28:29]
	s_mov_b32 m0, s38
	s_nop 0
	global_load_lds_dwordx4 v176, s[100:101]
	s_mov_b32 m0, s39
	s_nop 0
	global_load_lds_dwordx4 v180, s[100:101]
	s_waitcnt vmcnt(8)
	s_waitcnt lgkmcnt(0)
	s_barrier
	s_setprio 1
	s_waitcnt lgkmcnt(0)
	v_mfma_f32_16x16x32_bf16 v[60:63], v[128:131], v[160:163], v[60:63]
	v_mfma_f32_16x16x32_bf16 v[56:59], v[136:139], v[160:163], v[56:59]
	v_mfma_f32_16x16x32_bf16 v[44:47], v[128:131], v[168:171], v[44:47]
	v_mfma_f32_16x16x32_bf16 v[40:43], v[136:139], v[168:171], v[40:43]
	v_mfma_f32_16x16x32_bf16 v[28:31], v[128:131], v[192:195], v[28:31]
	v_mfma_f32_16x16x32_bf16 v[24:27], v[136:139], v[192:195], v[24:27]
	v_mfma_f32_16x16x32_bf16 v[12:15], v[128:131], v[200:203], v[12:15]
	v_mfma_f32_16x16x32_bf16 v[8:11], v[136:139], v[200:203], v[8:11]
	v_mfma_f32_16x16x32_bf16 v[60:63], v[132:135], v[164:167], v[60:63]
	v_mfma_f32_16x16x32_bf16 v[56:59], v[140:143], v[164:167], v[56:59]
	v_mfma_f32_16x16x32_bf16 v[44:47], v[132:135], v[172:175], v[44:47]
	v_mfma_f32_16x16x32_bf16 v[40:43], v[140:143], v[172:175], v[40:43]
	v_mfma_f32_16x16x32_bf16 v[28:31], v[132:135], v[196:199], v[28:31]
	v_mfma_f32_16x16x32_bf16 v[24:27], v[140:143], v[196:199], v[24:27]
	v_mfma_f32_16x16x32_bf16 v[12:15], v[132:135], v[212:215], v[12:15]
	v_mfma_f32_16x16x32_bf16 v[8:11], v[140:143], v[212:215], v[8:11]
	s_setprio 0
	s_setprio 1
	v_mfma_f32_16x16x32_bf16 v[52:55], v[144:147], v[160:163], v[52:55]
	v_mfma_f32_16x16x32_bf16 v[48:51], v[152:155], v[160:163], v[48:51]
	v_mfma_f32_16x16x32_bf16 v[36:39], v[144:147], v[168:171], v[36:39]
	v_mfma_f32_16x16x32_bf16 v[32:35], v[152:155], v[168:171], v[32:35]
	v_mfma_f32_16x16x32_bf16 v[20:23], v[144:147], v[192:195], v[20:23]
	v_mfma_f32_16x16x32_bf16 v[16:19], v[152:155], v[192:195], v[16:19]
	v_mfma_f32_16x16x32_bf16 v[4:7], v[144:147], v[200:203], v[4:7]
	v_mfma_f32_16x16x32_bf16 v[0:3], v[152:155], v[200:203], v[0:3]
	v_mfma_f32_16x16x32_bf16 v[52:55], v[148:151], v[164:167], v[52:55]
	v_mfma_f32_16x16x32_bf16 v[48:51], v[156:159], v[164:167], v[48:51]
	v_mfma_f32_16x16x32_bf16 v[36:39], v[148:151], v[172:175], v[36:39]
	v_mfma_f32_16x16x32_bf16 v[32:35], v[156:159], v[172:175], v[32:35]
	v_mfma_f32_16x16x32_bf16 v[20:23], v[148:151], v[196:199], v[20:23]
	v_mfma_f32_16x16x32_bf16 v[16:19], v[156:159], v[196:199], v[16:19]
	v_mfma_f32_16x16x32_bf16 v[4:7], v[148:151], v[212:215], v[4:7]
	v_mfma_f32_16x16x32_bf16 v[0:3], v[156:159], v[212:215], v[0:3]
	s_setprio 0
	s_barrier
	s_add_i32 s55, s55, 2
	s_add_u32 s26, s26, 0x100
	s_addc_u32 s27, s27, 0
	s_add_u32 s53, s53, 0x100
	s_addc_u32 s54, s54, 0
	s_cmp_gt_u32 s55, 61
	s_cbranch_scc0 .LBB0_431

.LBB0_527:
	s_ashr_i32 s47, s46, 31
	s_lshl_b64 s[50:51], s[46:47], 21
	s_add_u32 s50, s42, s50
	s_addc_u32 s51, s43, s51
	s_and_b64 s[52:53], s[18:19], exec
	s_cselect_b32 s47, s51, s21
	s_cselect_b32 s57, s50, s20
	s_ashr_i32 s41, s40, 31
	s_lshl_b64 s[52:53], s[40:41], 21
	s_add_u32 s52, s76, s52
	s_addc_u32 s53, s77, s53
	s_and_b64 s[78:79], s[18:19], exec
	s_cselect_b32 s41, s53, s63
	s_cselect_b32 s59, s52, s62
	s_add_u32 s20, s20, 0x100080
	s_addc_u32 s21, s21, 0
	s_add_u32 s81, s62, 0x100
	s_addc_u32 s82, s63, 0
	s_mov_b32 s83, -2
	ds_read_b128 v[134:137], v200
	ds_read_b128 v[138:141], v200 offset:1024
	ds_read_b128 v[162:165], v200 offset:2048
	ds_read_b128 v[166:169], v200 offset:3072
	ds_read_b128 v[170:173], v201
	ds_read_b128 v[174:177], v201 offset:1024
	ds_read_b128 v[178:181], v201 offset:2048
	ds_read_b128 v[206:209], v201 offset:3072
	s_add_u32 s62, s20, 0xfff00080
	s_addc_u32 s63, s21, -1
	s_cmp_eq_u32 s83, 60
	s_cselect_b32 s79, s47, s63
	s_cselect_b32 s78, s57, s62
	s_cselect_b32 s63, s41, s82
	s_cselect_b32 s62, s59, s81
	s_add_u32 s98, s62, s30
	s_addc_u32 s99, s63, s31
	s_add_u32 s100, s78, s30
	s_addc_u32 s101, s79, s31
	s_add_i32 m0, s39, 0xc000
	ds_read_b128 v[210:213], v202
	ds_read_b128 v[214:217], v202 offset:1024
	ds_read_b128 v[218:221], v202 offset:2048
	ds_read_b128 v[222:225], v202 offset:3072
	ds_read_b128 v[226:229], v202 offset:4096
	ds_read_b128 v[230:233], v202 offset:5120
	ds_read_b128 v[234:237], v202 offset:6144
	ds_read_b128 v[238:241], v202 offset:7168
	global_load_lds_dwordx4 v154, s[20:21]
	s_add_i32 m0, s39, 0xe000
	s_nop 0
	global_load_lds_dwordx4 v156, s[20:21]
	s_waitcnt vmcnt(8)
	s_waitcnt lgkmcnt(0)
	s_barrier
	s_setprio 1
	s_waitcnt lgkmcnt(0)
	v_mfma_f32_16x16x32_bf16 v[130:133], v[210:213], v[134:137], 0
	v_mfma_f32_16x16x32_bf16 v[126:129], v[210:213], v[162:165], 0
	v_mfma_f32_16x16x32_bf16 v[122:125], v[218:221], v[134:137], 0
	v_mfma_f32_16x16x32_bf16 v[118:121], v[218:221], v[162:165], 0
	v_mfma_f32_16x16x32_bf16 v[114:117], v[226:229], v[134:137], 0
	v_mfma_f32_16x16x32_bf16 v[110:113], v[226:229], v[162:165], 0
	v_mfma_f32_16x16x32_bf16 v[106:109], v[234:237], v[134:137], 0
	v_mfma_f32_16x16x32_bf16 v[102:105], v[234:237], v[162:165], 0
	v_mfma_f32_16x16x32_bf16 v[130:133], v[214:217], v[138:141], v[130:133]
	v_mfma_f32_16x16x32_bf16 v[126:129], v[214:217], v[166:169], v[126:129]
	v_mfma_f32_16x16x32_bf16 v[122:125], v[222:225], v[138:141], v[122:125]
	v_mfma_f32_16x16x32_bf16 v[118:121], v[222:225], v[166:169], v[118:121]
	v_mfma_f32_16x16x32_bf16 v[114:117], v[230:233], v[138:141], v[114:117]
	v_mfma_f32_16x16x32_bf16 v[110:113], v[230:233], v[166:169], v[110:113]
	v_mfma_f32_16x16x32_bf16 v[106:109], v[238:241], v[138:141], v[106:109]
	v_mfma_f32_16x16x32_bf16 v[102:105], v[238:241], v[166:169], v[102:105]
	s_setprio 0
	s_setprio 1
	v_mfma_f32_16x16x32_bf16 v[64:67], v[170:173], v[210:213], 0
	v_mfma_f32_16x16x32_bf16 v[60:63], v[178:181], v[210:213], 0
	v_mfma_f32_16x16x32_bf16 v[56:59], v[170:173], v[218:221], 0
	v_mfma_f32_16x16x32_bf16 v[52:55], v[178:181], v[218:221], 0
	v_mfma_f32_16x16x32_bf16 v[48:51], v[170:173], v[226:229], 0
	v_mfma_f32_16x16x32_bf16 v[44:47], v[178:181], v[226:229], 0
	v_mfma_f32_16x16x32_bf16 v[40:43], v[170:173], v[234:237], 0
	v_mfma_f32_16x16x32_bf16 v[36:39], v[178:181], v[234:237], 0
	v_mfma_f32_16x16x32_bf16 v[64:67], v[174:177], v[214:217], v[64:67]
	v_mfma_f32_16x16x32_bf16 v[60:63], v[206:209], v[214:217], v[60:63]
	v_mfma_f32_16x16x32_bf16 v[56:59], v[174:177], v[222:225], v[56:59]
	v_mfma_f32_16x16x32_bf16 v[52:55], v[206:209], v[222:225], v[52:55]
	v_mfma_f32_16x16x32_bf16 v[48:51], v[174:177], v[230:233], v[48:51]
	v_mfma_f32_16x16x32_bf16 v[44:47], v[206:209], v[230:233], v[44:47]
	v_mfma_f32_16x16x32_bf16 v[40:43], v[174:177], v[238:241], v[40:43]
	v_mfma_f32_16x16x32_bf16 v[36:39], v[206:209], v[238:241], v[36:39]
	s_setprio 0
	s_barrier
	s_add_i32 s84, s75, s3
	s_mov_b32 m0, s84
	ds_read_b128 v[210:213], v202 offset:16384
	ds_read_b128 v[214:217], v202 offset:17408
	ds_read_b128 v[218:221], v202 offset:18432
	ds_read_b128 v[222:225], v202 offset:19456
	ds_read_b128 v[226:229], v202 offset:20480
	ds_read_b128 v[230:233], v202 offset:21504
	ds_read_b128 v[234:237], v202 offset:22528
	ds_read_b128 v[238:241], v202 offset:23552
	global_load_lds_dwordx4 v144, s[62:63]
	s_add_i32 m0, s84, 0x2000
	s_add_u32 s84, s62, 0x100000
	s_addc_u32 s85, s63, 0
	s_add_i32 s86, s80, s3
	global_load_lds_dwordx4 v148, s[62:63]
	s_mov_b32 m0, s86
	s_nop 0
	global_load_lds_dwordx4 v144, s[84:85]
	s_add_i32 m0, s86, 0x2000
	s_nop 0
	global_load_lds_dwordx4 v148, s[84:85]
	s_mov_b32 m0, s39
	s_nop 0
	global_load_lds_dwordx4 v142, s[78:79]
	s_mov_b32 m0, s54
	s_nop 0
	global_load_lds_dwordx4 v146, s[78:79]
	s_waitcnt vmcnt(8)
	s_waitcnt lgkmcnt(0)
	s_barrier
	s_setprio 1
	s_waitcnt lgkmcnt(0)
	v_mfma_f32_16x16x32_bf16 v[98:101], v[210:213], v[134:137], 0
	v_mfma_f32_16x16x32_bf16 v[94:97], v[210:213], v[162:165], 0
	v_mfma_f32_16x16x32_bf16 v[90:93], v[218:221], v[134:137], 0
	v_mfma_f32_16x16x32_bf16 v[86:89], v[218:221], v[162:165], 0
	v_mfma_f32_16x16x32_bf16 v[82:85], v[226:229], v[134:137], 0
	v_mfma_f32_16x16x32_bf16 v[68:71], v[226:229], v[162:165], 0
	v_mfma_f32_16x16x32_bf16 v[72:75], v[234:237], v[134:137], 0
	v_mfma_f32_16x16x32_bf16 v[76:79], v[234:237], v[162:165], 0
	v_mfma_f32_16x16x32_bf16 v[98:101], v[214:217], v[138:141], v[98:101]
	v_mfma_f32_16x16x32_bf16 v[94:97], v[214:217], v[166:169], v[94:97]
	v_mfma_f32_16x16x32_bf16 v[90:93], v[222:225], v[138:141], v[90:93]
	v_mfma_f32_16x16x32_bf16 v[86:89], v[222:225], v[166:169], v[86:89]
	v_mfma_f32_16x16x32_bf16 v[82:85], v[230:233], v[138:141], v[82:85]
	v_mfma_f32_16x16x32_bf16 v[68:71], v[230:233], v[166:169], v[68:71]
	v_mfma_f32_16x16x32_bf16 v[72:75], v[238:241], v[138:141], v[72:75]
	v_mfma_f32_16x16x32_bf16 v[78:81], v[238:241], v[166:169], v[76:79]
	s_setprio 0
	s_setprio 1
	v_mfma_f32_16x16x32_bf16 v[32:35], v[170:173], v[210:213], 0
	v_mfma_f32_16x16x32_bf16 v[28:31], v[178:181], v[210:213], 0
	v_mfma_f32_16x16x32_bf16 v[24:27], v[170:173], v[218:221], 0
	v_mfma_f32_16x16x32_bf16 v[20:23], v[178:181], v[218:221], 0
	v_mfma_f32_16x16x32_bf16 v[16:19], v[170:173], v[226:229], 0
	v_mfma_f32_16x16x32_bf16 v[12:15], v[178:181], v[226:229], 0
	v_mfma_f32_16x16x32_bf16 v[2:5], v[170:173], v[234:237], 0
	v_mfma_f32_16x16x32_bf16 v[6:9], v[178:181], v[234:237], 0
	v_mfma_f32_16x16x32_bf16 v[32:35], v[174:177], v[214:217], v[32:35]
	v_mfma_f32_16x16x32_bf16 v[28:31], v[206:209], v[214:217], v[28:31]
	v_mfma_f32_16x16x32_bf16 v[24:27], v[174:177], v[222:225], v[24:27]
	v_mfma_f32_16x16x32_bf16 v[20:23], v[206:209], v[222:225], v[20:23]
	v_mfma_f32_16x16x32_bf16 v[16:19], v[174:177], v[230:233], v[16:19]
	v_mfma_f32_16x16x32_bf16 v[12:15], v[206:209], v[230:233], v[12:15]
	v_mfma_f32_16x16x32_bf16 v[2:5], v[174:177], v[238:241], v[2:5]
	v_mfma_f32_16x16x32_bf16 v[8:11], v[206:209], v[238:241], v[6:9]
	s_setprio 0
	s_barrier
	s_add_i32 s84, 0, 0x18000
	v_add_u32_e32 v1, s84, v183
	s_add_i32 s85, 0, 0x1c000
	ds_read_b128 v[134:137], v1
	ds_read_b128 v[138:141], v1 offset:1024
	ds_read_b128 v[162:165], v1 offset:2048
	ds_read_b128 v[166:169], v1 offset:3072
	v_add_u32_e32 v1, s85, v183
	ds_read_b128 v[170:173], v1
	ds_read_b128 v[174:177], v1 offset:1024
	ds_read_b128 v[178:181], v1 offset:2048
	ds_read_b128 v[206:209], v1 offset:3072
	s_add_u32 s78, s78, 0x100000
	s_addc_u32 s79, s79, 0
	s_mov_b32 m0, s55
	ds_read_b128 v[210:213], v202 offset:32768
	ds_read_b128 v[214:217], v202 offset:33792
	ds_read_b128 v[218:221], v202 offset:34816
	ds_read_b128 v[222:225], v202 offset:35840
	ds_read_b128 v[226:229], v202 offset:36864
	ds_read_b128 v[230:233], v202 offset:37888
	ds_read_b128 v[234:237], v202 offset:38912
	ds_read_b128 v[238:241], v202 offset:39936
	global_load_lds_dwordx4 v142, s[78:79]
	s_mov_b32 m0, s68
	s_nop 0
	global_load_lds_dwordx4 v146, s[78:79]
	s_waitcnt vmcnt(8)
	s_waitcnt lgkmcnt(0)
	s_barrier
	s_setprio 1
	s_waitcnt lgkmcnt(0)
	v_mfma_f32_16x16x32_bf16 v[130:133], v[210:213], v[134:137], v[130:133]
	v_mfma_f32_16x16x32_bf16 v[126:129], v[210:213], v[162:165], v[126:129]
	v_mfma_f32_16x16x32_bf16 v[122:125], v[218:221], v[134:137], v[122:125]
	v_mfma_f32_16x16x32_bf16 v[118:121], v[218:221], v[162:165], v[118:121]
	v_mfma_f32_16x16x32_bf16 v[114:117], v[226:229], v[134:137], v[114:117]
	v_mfma_f32_16x16x32_bf16 v[110:113], v[226:229], v[162:165], v[110:113]
	v_mfma_f32_16x16x32_bf16 v[106:109], v[234:237], v[134:137], v[106:109]
	v_mfma_f32_16x16x32_bf16 v[102:105], v[234:237], v[162:165], v[102:105]
	v_mfma_f32_16x16x32_bf16 v[130:133], v[214:217], v[138:141], v[130:133]
	v_mfma_f32_16x16x32_bf16 v[126:129], v[214:217], v[166:169], v[126:129]
	v_mfma_f32_16x16x32_bf16 v[122:125], v[222:225], v[138:141], v[122:125]
	v_mfma_f32_16x16x32_bf16 v[118:121], v[222:225], v[166:169], v[118:121]
	v_mfma_f32_16x16x32_bf16 v[114:117], v[230:233], v[138:141], v[114:117]
	v_mfma_f32_16x16x32_bf16 v[110:113], v[230:233], v[166:169], v[110:113]
	v_mfma_f32_16x16x32_bf16 v[106:109], v[238:241], v[138:141], v[106:109]
	v_mfma_f32_16x16x32_bf16 v[102:105], v[238:241], v[166:169], v[102:105]
	s_setprio 0
	s_setprio 1
	v_mfma_f32_16x16x32_bf16 v[64:67], v[170:173], v[210:213], v[64:67]
	v_mfma_f32_16x16x32_bf16 v[60:63], v[178:181], v[210:213], v[60:63]
	v_mfma_f32_16x16x32_bf16 v[56:59], v[170:173], v[218:221], v[56:59]
	v_mfma_f32_16x16x32_bf16 v[52:55], v[178:181], v[218:221], v[52:55]
	v_mfma_f32_16x16x32_bf16 v[48:51], v[170:173], v[226:229], v[48:51]
	v_mfma_f32_16x16x32_bf16 v[44:47], v[178:181], v[226:229], v[44:47]
	v_mfma_f32_16x16x32_bf16 v[40:43], v[170:173], v[234:237], v[40:43]
	v_mfma_f32_16x16x32_bf16 v[36:39], v[178:181], v[234:237], v[36:39]
	v_mfma_f32_16x16x32_bf16 v[64:67], v[174:177], v[214:217], v[64:67]
	v_mfma_f32_16x16x32_bf16 v[60:63], v[206:209], v[214:217], v[60:63]
	v_mfma_f32_16x16x32_bf16 v[56:59], v[174:177], v[222:225], v[56:59]
	v_mfma_f32_16x16x32_bf16 v[52:55], v[206:209], v[222:225], v[52:55]
	v_mfma_f32_16x16x32_bf16 v[48:51], v[174:177], v[230:233], v[48:51]
	v_mfma_f32_16x16x32_bf16 v[44:47], v[206:209], v[230:233], v[44:47]
	v_mfma_f32_16x16x32_bf16 v[40:43], v[174:177], v[238:241], v[40:43]
	v_mfma_f32_16x16x32_bf16 v[36:39], v[206:209], v[238:241], v[36:39]
	s_setprio 0
	s_barrier
	s_add_i32 s78, s84, s3
	s_mov_b32 m0, s78
	ds_read_b128 v[210:213], v202 offset:49152
	ds_read_b128 v[214:217], v202 offset:50176
	ds_read_b128 v[218:221], v202 offset:51200
	ds_read_b128 v[222:225], v202 offset:52224
	ds_read_b128 v[226:229], v202 offset:53248
	ds_read_b128 v[230:233], v202 offset:54272
	ds_read_b128 v[234:237], v202 offset:55296
	ds_read_b128 v[238:241], v202 offset:56320
	global_load_lds_dwordx4 v144, s[98:99]
	s_add_i32 m0, s78, 0x2000
	s_add_u32 s62, s62, 0x100080
	s_addc_u32 s63, s63, 0
	s_add_i32 s78, s85, s3
	global_load_lds_dwordx4 v148, s[98:99]
	s_mov_b32 m0, s78
	s_nop 0
	global_load_lds_dwordx4 v144, s[62:63]
	s_add_i32 m0, s78, 0x2000
	s_nop 0
	global_load_lds_dwordx4 v148, s[62:63]
	s_mov_b32 m0, s71
	s_nop 0
	global_load_lds_dwordx4 v142, s[100:101]
	s_mov_b32 m0, s72
	s_nop 0
	global_load_lds_dwordx4 v146, s[100:101]
	s_waitcnt vmcnt(8)
	s_waitcnt lgkmcnt(0)
	s_barrier
	s_setprio 1
	s_waitcnt lgkmcnt(0)
	v_mfma_f32_16x16x32_bf16 v[98:101], v[210:213], v[134:137], v[98:101]
	v_mfma_f32_16x16x32_bf16 v[94:97], v[210:213], v[162:165], v[94:97]
	v_mfma_f32_16x16x32_bf16 v[90:93], v[218:221], v[134:137], v[90:93]
	v_mfma_f32_16x16x32_bf16 v[86:89], v[218:221], v[162:165], v[86:89]
	v_mfma_f32_16x16x32_bf16 v[82:85], v[226:229], v[134:137], v[82:85]
	v_mfma_f32_16x16x32_bf16 v[68:71], v[226:229], v[162:165], v[68:71]
	v_mfma_f32_16x16x32_bf16 v[72:75], v[234:237], v[134:137], v[72:75]
	v_mfma_f32_16x16x32_bf16 v[78:81], v[234:237], v[162:165], v[78:81]
	v_mfma_f32_16x16x32_bf16 v[98:101], v[214:217], v[138:141], v[98:101]
	v_mfma_f32_16x16x32_bf16 v[94:97], v[214:217], v[166:169], v[94:97]
	v_mfma_f32_16x16x32_bf16 v[90:93], v[222:225], v[138:141], v[90:93]
	v_mfma_f32_16x16x32_bf16 v[86:89], v[222:225], v[166:169], v[86:89]
	v_mfma_f32_16x16x32_bf16 v[82:85], v[230:233], v[138:141], v[82:85]
	v_mfma_f32_16x16x32_bf16 v[68:71], v[230:233], v[166:169], v[68:71]
	v_mfma_f32_16x16x32_bf16 v[74:77], v[238:241], v[138:141], v[72:75]
	v_mfma_f32_16x16x32_bf16 v[78:81], v[238:241], v[166:169], v[78:81]
	s_setprio 0
	s_setprio 1
	v_mfma_f32_16x16x32_bf16 v[32:35], v[170:173], v[210:213], v[32:35]
	v_mfma_f32_16x16x32_bf16 v[28:31], v[178:181], v[210:213], v[28:31]
	v_mfma_f32_16x16x32_bf16 v[24:27], v[170:173], v[218:221], v[24:27]
	v_mfma_f32_16x16x32_bf16 v[20:23], v[178:181], v[218:221], v[20:23]
	v_mfma_f32_16x16x32_bf16 v[16:19], v[170:173], v[226:229], v[16:19]
	v_mfma_f32_16x16x32_bf16 v[12:15], v[178:181], v[226:229], v[12:15]
	v_mfma_f32_16x16x32_bf16 v[2:5], v[170:173], v[234:237], v[2:5]
	v_mfma_f32_16x16x32_bf16 v[8:11], v[178:181], v[234:237], v[8:11]
	v_mfma_f32_16x16x32_bf16 v[32:35], v[174:177], v[214:217], v[32:35]
	v_mfma_f32_16x16x32_bf16 v[28:31], v[206:209], v[214:217], v[28:31]
	v_mfma_f32_16x16x32_bf16 v[24:27], v[174:177], v[222:225], v[24:27]
	v_mfma_f32_16x16x32_bf16 v[20:23], v[206:209], v[222:225], v[20:23]
	v_mfma_f32_16x16x32_bf16 v[16:19], v[174:177], v[230:233], v[16:19]
	v_mfma_f32_16x16x32_bf16 v[12:15], v[206:209], v[230:233], v[12:15]
	v_mfma_f32_16x16x32_bf16 v[4:7], v[174:177], v[238:241], v[2:5]
	v_mfma_f32_16x16x32_bf16 v[8:11], v[206:209], v[238:241], v[8:11]
	s_setprio 0
	s_barrier
	s_add_i32 s83, s83, 2
	s_add_u32 s20, s20, 0x100
	s_addc_u32 s21, s21, 0
	s_add_u32 s81, s81, 0x100
	s_addc_u32 s82, s82, 0
	s_cmp_gt_u32 s83, 61
	s_cbranch_scc0 .LBB0_528

.LBB0_814:
	s_ashr_i32 s29, s28, 31
	s_lshl_b64 s[34:35], s[28:29], 22
	s_add_u32 s34, s48, s34
	s_addc_u32 s35, s49, s35
	s_and_b64 s[36:37], s[4:5], exec
	s_cselect_b32 s29, s35, s47
	s_cselect_b32 s39, s34, s46
	s_ashr_i32 s31, s30, 31
	s_lshl_b64 s[36:37], s[30:31], 22
	v_readlane_b32 s52, v254, 7
	v_readlane_b32 s53, v254, 8
	s_add_u32 s36, s52, s36
	s_addc_u32 s37, s53, s37
	s_and_b64 s[52:53], s[4:5], exec
	s_cselect_b32 s31, s37, s51
	s_cselect_b32 s41, s36, s50
	s_add_u32 s46, s46, 0x200080
	s_addc_u32 s47, s47, 0
	s_add_u32 s75, s50, 0x100
	s_addc_u32 s76, s51, 0
	s_mov_b32 s77, -2
	ds_read_b128 v[56:59], v241
	ds_read_b128 v[60:63], v241 offset:1024
	ds_read_b128 v[64:67], v241 offset:2048
	ds_read_b128 v[68:71], v241 offset:3072
	ds_read_b128 v[144:147], v242
	ds_read_b128 v[148:151], v242 offset:1024
	ds_read_b128 v[152:155], v242 offset:2048
	ds_read_b128 v[156:159], v242 offset:3072
	s_add_u32 s50, s46, 0xffe00080
	s_addc_u32 s51, s47, -1
	s_cmpk_eq_i32 s77, 0x7c
	s_cselect_b32 s53, s29, s51
	s_cselect_b32 s52, s39, s50
	s_cselect_b32 s51, s31, s76
	s_cselect_b32 s50, s41, s75
	s_add_u32 s98, s50, s12
	s_addc_u32 s99, s51, s13
	s_add_u32 s100, s52, s12
	s_addc_u32 s101, s53, s13
	s_add_i32 m0, s55, 0xc000
	ds_read_b128 v[160:163], v243
	ds_read_b128 v[164:167], v243 offset:1024
	ds_read_b128 v[168:171], v243 offset:2048
	ds_read_b128 v[172:175], v243 offset:3072
	ds_read_b128 v[176:179], v243 offset:4096
	ds_read_b128 v[180:183], v243 offset:5120
	ds_read_b128 v[184:187], v243 offset:6144
	ds_read_b128 v[188:191], v243 offset:7168
	global_load_lds_dwordx4 v216, s[46:47]
	s_add_i32 m0, s55, 0xe000
	s_nop 0
	global_load_lds_dwordx4 v218, s[46:47]
	s_waitcnt vmcnt(8)
	s_waitcnt lgkmcnt(0)
	s_barrier
	s_setprio 1
	s_waitcnt lgkmcnt(0)
	v_mfma_f32_16x16x32_bf16 v[140:143], v[56:59], v[160:163], 0
	v_mfma_f32_16x16x32_bf16 v[136:139], v[64:67], v[160:163], 0
	v_mfma_f32_16x16x32_bf16 v[124:127], v[56:59], v[168:171], 0
	v_mfma_f32_16x16x32_bf16 v[120:123], v[64:67], v[168:171], 0
	v_mfma_f32_16x16x32_bf16 v[108:111], v[56:59], v[176:179], 0
	v_mfma_f32_16x16x32_bf16 v[104:107], v[64:67], v[176:179], 0
	v_mfma_f32_16x16x32_bf16 v[92:95], v[56:59], v[184:187], 0
	v_mfma_f32_16x16x32_bf16 v[88:91], v[64:67], v[184:187], 0
	v_mfma_f32_16x16x32_bf16 v[140:143], v[60:63], v[164:167], v[140:143]
	v_mfma_f32_16x16x32_bf16 v[136:139], v[68:71], v[164:167], v[136:139]
	v_mfma_f32_16x16x32_bf16 v[124:127], v[60:63], v[172:175], v[124:127]
	v_mfma_f32_16x16x32_bf16 v[120:123], v[68:71], v[172:175], v[120:123]
	v_mfma_f32_16x16x32_bf16 v[108:111], v[60:63], v[180:183], v[108:111]
	v_mfma_f32_16x16x32_bf16 v[104:107], v[68:71], v[180:183], v[104:107]
	v_mfma_f32_16x16x32_bf16 v[92:95], v[60:63], v[188:191], v[92:95]
	v_mfma_f32_16x16x32_bf16 v[88:91], v[68:71], v[188:191], v[88:91]
	s_setprio 0
	s_setprio 1
	v_mfma_f32_16x16x32_bf16 v[132:135], v[144:147], v[160:163], 0
	v_mfma_f32_16x16x32_bf16 v[128:131], v[152:155], v[160:163], 0
	v_mfma_f32_16x16x32_bf16 v[116:119], v[144:147], v[168:171], 0
	v_mfma_f32_16x16x32_bf16 v[112:115], v[152:155], v[168:171], 0
	v_mfma_f32_16x16x32_bf16 v[100:103], v[144:147], v[176:179], 0
	v_mfma_f32_16x16x32_bf16 v[96:99], v[152:155], v[176:179], 0
	v_mfma_f32_16x16x32_bf16 v[84:87], v[144:147], v[184:187], 0
	v_mfma_f32_16x16x32_bf16 v[80:83], v[152:155], v[184:187], 0
	v_mfma_f32_16x16x32_bf16 v[132:135], v[148:151], v[164:167], v[132:135]
	v_mfma_f32_16x16x32_bf16 v[128:131], v[156:159], v[164:167], v[128:131]
	v_mfma_f32_16x16x32_bf16 v[116:119], v[148:151], v[172:175], v[116:119]
	v_mfma_f32_16x16x32_bf16 v[112:115], v[156:159], v[172:175], v[112:115]
	v_mfma_f32_16x16x32_bf16 v[100:103], v[148:151], v[180:183], v[100:103]
	v_mfma_f32_16x16x32_bf16 v[96:99], v[156:159], v[180:183], v[96:99]
	v_mfma_f32_16x16x32_bf16 v[84:87], v[148:151], v[188:191], v[84:87]
	v_mfma_f32_16x16x32_bf16 v[80:83], v[156:159], v[188:191], v[80:83]
	s_setprio 0
	s_barrier
	s_add_i32 s78, s73, s54
	s_mov_b32 m0, s78
	ds_read_b128 v[160:163], v243 offset:16384
	ds_read_b128 v[164:167], v243 offset:17408
	ds_read_b128 v[168:171], v243 offset:18432
	ds_read_b128 v[172:175], v243 offset:19456
	ds_read_b128 v[176:179], v243 offset:20480
	ds_read_b128 v[180:183], v243 offset:21504
	ds_read_b128 v[184:187], v243 offset:22528
	ds_read_b128 v[188:191], v243 offset:23552
	global_load_lds_dwordx4 v210, s[50:51]
	s_add_i32 m0, s78, 0x2000
	s_add_u32 s78, s50, 0x200000
	s_addc_u32 s79, s51, 0
	s_add_i32 s80, s74, s54
	global_load_lds_dwordx4 v214, s[50:51]
	s_mov_b32 m0, s80
	s_nop 0
	global_load_lds_dwordx4 v210, s[78:79]
	s_add_i32 m0, s80, 0x2000
	s_nop 0
	global_load_lds_dwordx4 v214, s[78:79]
	s_mov_b32 m0, s55
	s_nop 0
	global_load_lds_dwordx4 v208, s[52:53]
	s_mov_b32 m0, s56
	s_nop 0
	global_load_lds_dwordx4 v212, s[52:53]
	s_waitcnt vmcnt(8)
	s_waitcnt lgkmcnt(0)
	s_barrier
	s_setprio 1
	s_waitcnt lgkmcnt(0)
	v_mfma_f32_16x16x32_bf16 v[76:79], v[56:59], v[160:163], 0
	v_mfma_f32_16x16x32_bf16 v[72:75], v[64:67], v[160:163], 0
	v_mfma_f32_16x16x32_bf16 v[44:47], v[56:59], v[168:171], 0
	v_mfma_f32_16x16x32_bf16 v[40:43], v[64:67], v[168:171], 0
	v_mfma_f32_16x16x32_bf16 v[28:31], v[56:59], v[176:179], 0
	v_mfma_f32_16x16x32_bf16 v[24:27], v[64:67], v[176:179], 0
	v_mfma_f32_16x16x32_bf16 v[12:15], v[56:59], v[184:187], 0
	v_mfma_f32_16x16x32_bf16 v[8:11], v[64:67], v[184:187], 0
	v_mfma_f32_16x16x32_bf16 v[76:79], v[60:63], v[164:167], v[76:79]
	v_mfma_f32_16x16x32_bf16 v[72:75], v[68:71], v[164:167], v[72:75]
	v_mfma_f32_16x16x32_bf16 v[44:47], v[60:63], v[172:175], v[44:47]
	v_mfma_f32_16x16x32_bf16 v[40:43], v[68:71], v[172:175], v[40:43]
	v_mfma_f32_16x16x32_bf16 v[28:31], v[60:63], v[180:183], v[28:31]
	v_mfma_f32_16x16x32_bf16 v[24:27], v[68:71], v[180:183], v[24:27]
	v_mfma_f32_16x16x32_bf16 v[12:15], v[60:63], v[188:191], v[12:15]
	v_mfma_f32_16x16x32_bf16 v[8:11], v[68:71], v[188:191], v[8:11]
	s_setprio 0
	s_setprio 1
	v_mfma_f32_16x16x32_bf16 v[52:55], v[144:147], v[160:163], 0
	v_mfma_f32_16x16x32_bf16 v[48:51], v[152:155], v[160:163], 0
	v_mfma_f32_16x16x32_bf16 v[36:39], v[144:147], v[168:171], 0
	v_mfma_f32_16x16x32_bf16 v[32:35], v[152:155], v[168:171], 0
	v_mfma_f32_16x16x32_bf16 v[20:23], v[144:147], v[176:179], 0
	v_mfma_f32_16x16x32_bf16 v[16:19], v[152:155], v[176:179], 0
	v_mfma_f32_16x16x32_bf16 v[4:7], v[144:147], v[184:187], 0
	v_mfma_f32_16x16x32_bf16 v[0:3], v[152:155], v[184:187], 0
	v_mfma_f32_16x16x32_bf16 v[52:55], v[148:151], v[164:167], v[52:55]
	v_mfma_f32_16x16x32_bf16 v[48:51], v[156:159], v[164:167], v[48:51]
	v_mfma_f32_16x16x32_bf16 v[36:39], v[148:151], v[172:175], v[36:39]
	v_mfma_f32_16x16x32_bf16 v[32:35], v[156:159], v[172:175], v[32:35]
	v_mfma_f32_16x16x32_bf16 v[20:23], v[148:151], v[180:183], v[20:23]
	v_mfma_f32_16x16x32_bf16 v[16:19], v[156:159], v[180:183], v[16:19]
	v_mfma_f32_16x16x32_bf16 v[4:7], v[148:151], v[188:191], v[4:7]
	v_mfma_f32_16x16x32_bf16 v[0:3], v[156:159], v[188:191], v[0:3]
	s_setprio 0
	s_barrier
	s_add_i32 s78, 0, 0x18000
	s_add_i32 s79, 0, 0x1c000
	v_add_u32_e32 v68, s78, v239
	v_add_u32_e32 v156, s79, v239
	ds_read_b128 v[56:59], v68
	ds_read_b128 v[60:63], v68 offset:1024
	ds_read_b128 v[64:67], v68 offset:2048
	ds_read_b128 v[68:71], v68 offset:3072
	ds_read_b128 v[144:147], v156
	ds_read_b128 v[148:151], v156 offset:1024
	ds_read_b128 v[152:155], v156 offset:2048
	ds_read_b128 v[156:159], v156 offset:3072
	s_add_u32 s52, s52, 0x200000
	s_addc_u32 s53, s53, 0
	s_mov_b32 m0, s57
	ds_read_b128 v[160:163], v243 offset:32768
	ds_read_b128 v[164:167], v243 offset:33792
	ds_read_b128 v[168:171], v243 offset:34816
	ds_read_b128 v[172:175], v243 offset:35840
	ds_read_b128 v[176:179], v243 offset:36864
	ds_read_b128 v[180:183], v243 offset:37888
	ds_read_b128 v[184:187], v243 offset:38912
	ds_read_b128 v[188:191], v243 offset:39936
	global_load_lds_dwordx4 v208, s[52:53]
	s_mov_b32 m0, s58
	s_nop 0
	global_load_lds_dwordx4 v212, s[52:53]
	s_waitcnt vmcnt(8)
	s_waitcnt lgkmcnt(0)
	s_barrier
	s_setprio 1
	s_waitcnt lgkmcnt(0)
	v_mfma_f32_16x16x32_bf16 v[140:143], v[56:59], v[160:163], v[140:143]
	v_mfma_f32_16x16x32_bf16 v[136:139], v[64:67], v[160:163], v[136:139]
	v_mfma_f32_16x16x32_bf16 v[124:127], v[56:59], v[168:171], v[124:127]
	v_mfma_f32_16x16x32_bf16 v[120:123], v[64:67], v[168:171], v[120:123]
	v_mfma_f32_16x16x32_bf16 v[108:111], v[56:59], v[176:179], v[108:111]
	v_mfma_f32_16x16x32_bf16 v[104:107], v[64:67], v[176:179], v[104:107]
	v_mfma_f32_16x16x32_bf16 v[92:95], v[56:59], v[184:187], v[92:95]
	v_mfma_f32_16x16x32_bf16 v[88:91], v[64:67], v[184:187], v[88:91]
	v_mfma_f32_16x16x32_bf16 v[140:143], v[60:63], v[164:167], v[140:143]
	v_mfma_f32_16x16x32_bf16 v[136:139], v[68:71], v[164:167], v[136:139]
	v_mfma_f32_16x16x32_bf16 v[124:127], v[60:63], v[172:175], v[124:127]
	v_mfma_f32_16x16x32_bf16 v[120:123], v[68:71], v[172:175], v[120:123]
	v_mfma_f32_16x16x32_bf16 v[108:111], v[60:63], v[180:183], v[108:111]
	v_mfma_f32_16x16x32_bf16 v[104:107], v[68:71], v[180:183], v[104:107]
	v_mfma_f32_16x16x32_bf16 v[92:95], v[60:63], v[188:191], v[92:95]
	v_mfma_f32_16x16x32_bf16 v[88:91], v[68:71], v[188:191], v[88:91]
	s_setprio 0
	s_setprio 1
	v_mfma_f32_16x16x32_bf16 v[132:135], v[144:147], v[160:163], v[132:135]
	v_mfma_f32_16x16x32_bf16 v[128:131], v[152:155], v[160:163], v[128:131]
	v_mfma_f32_16x16x32_bf16 v[116:119], v[144:147], v[168:171], v[116:119]
	v_mfma_f32_16x16x32_bf16 v[112:115], v[152:155], v[168:171], v[112:115]
	v_mfma_f32_16x16x32_bf16 v[100:103], v[144:147], v[176:179], v[100:103]
	v_mfma_f32_16x16x32_bf16 v[96:99], v[152:155], v[176:179], v[96:99]
	v_mfma_f32_16x16x32_bf16 v[84:87], v[144:147], v[184:187], v[84:87]
	v_mfma_f32_16x16x32_bf16 v[80:83], v[152:155], v[184:187], v[80:83]
	v_mfma_f32_16x16x32_bf16 v[132:135], v[148:151], v[164:167], v[132:135]
	v_mfma_f32_16x16x32_bf16 v[128:131], v[156:159], v[164:167], v[128:131]
	v_mfma_f32_16x16x32_bf16 v[116:119], v[148:151], v[172:175], v[116:119]
	v_mfma_f32_16x16x32_bf16 v[112:115], v[156:159], v[172:175], v[112:115]
	v_mfma_f32_16x16x32_bf16 v[100:103], v[148:151], v[180:183], v[100:103]
	v_mfma_f32_16x16x32_bf16 v[96:99], v[156:159], v[180:183], v[96:99]
	v_mfma_f32_16x16x32_bf16 v[84:87], v[148:151], v[188:191], v[84:87]
	v_mfma_f32_16x16x32_bf16 v[80:83], v[156:159], v[188:191], v[80:83]
	s_setprio 0
	s_barrier
	s_add_i32 s52, s78, s54
	s_mov_b32 m0, s52
	ds_read_b128 v[160:163], v243 offset:49152
	ds_read_b128 v[164:167], v243 offset:50176
	ds_read_b128 v[168:171], v243 offset:51200
	ds_read_b128 v[172:175], v243 offset:52224
	ds_read_b128 v[176:179], v243 offset:53248
	ds_read_b128 v[180:183], v243 offset:54272
	ds_read_b128 v[184:187], v243 offset:55296
	ds_read_b128 v[188:191], v243 offset:56320
	global_load_lds_dwordx4 v210, s[98:99]
	s_add_i32 m0, s52, 0x2000
	s_add_u32 s50, s50, 0x200080
	s_addc_u32 s51, s51, 0
	s_add_i32 s52, s79, s54
	global_load_lds_dwordx4 v214, s[98:99]
	s_mov_b32 m0, s52
	s_nop 0
	global_load_lds_dwordx4 v210, s[50:51]
	s_add_i32 m0, s52, 0x2000
	s_nop 0
	global_load_lds_dwordx4 v214, s[50:51]
	s_mov_b32 m0, s63
	s_nop 0
	global_load_lds_dwordx4 v208, s[100:101]
	s_mov_b32 m0, s68
	s_nop 0
	global_load_lds_dwordx4 v212, s[100:101]
	s_waitcnt vmcnt(8)
	s_waitcnt lgkmcnt(0)
	s_barrier
	s_setprio 1
	s_waitcnt lgkmcnt(0)
	v_mfma_f32_16x16x32_bf16 v[76:79], v[56:59], v[160:163], v[76:79]
	v_mfma_f32_16x16x32_bf16 v[72:75], v[64:67], v[160:163], v[72:75]
	v_mfma_f32_16x16x32_bf16 v[44:47], v[56:59], v[168:171], v[44:47]
	v_mfma_f32_16x16x32_bf16 v[40:43], v[64:67], v[168:171], v[40:43]
	v_mfma_f32_16x16x32_bf16 v[28:31], v[56:59], v[176:179], v[28:31]
	v_mfma_f32_16x16x32_bf16 v[24:27], v[64:67], v[176:179], v[24:27]
	v_mfma_f32_16x16x32_bf16 v[12:15], v[56:59], v[184:187], v[12:15]
	v_mfma_f32_16x16x32_bf16 v[8:11], v[64:67], v[184:187], v[8:11]
	v_mfma_f32_16x16x32_bf16 v[76:79], v[60:63], v[164:167], v[76:79]
	v_mfma_f32_16x16x32_bf16 v[72:75], v[68:71], v[164:167], v[72:75]
	v_mfma_f32_16x16x32_bf16 v[44:47], v[60:63], v[172:175], v[44:47]
	v_mfma_f32_16x16x32_bf16 v[40:43], v[68:71], v[172:175], v[40:43]
	v_mfma_f32_16x16x32_bf16 v[28:31], v[60:63], v[180:183], v[28:31]
	v_mfma_f32_16x16x32_bf16 v[24:27], v[68:71], v[180:183], v[24:27]
	v_mfma_f32_16x16x32_bf16 v[12:15], v[60:63], v[188:191], v[12:15]
	v_mfma_f32_16x16x32_bf16 v[8:11], v[68:71], v[188:191], v[8:11]
	s_setprio 0
	s_setprio 1
	v_mfma_f32_16x16x32_bf16 v[52:55], v[144:147], v[160:163], v[52:55]
	v_mfma_f32_16x16x32_bf16 v[48:51], v[152:155], v[160:163], v[48:51]
	v_mfma_f32_16x16x32_bf16 v[36:39], v[144:147], v[168:171], v[36:39]
	v_mfma_f32_16x16x32_bf16 v[32:35], v[152:155], v[168:171], v[32:35]
	v_mfma_f32_16x16x32_bf16 v[20:23], v[144:147], v[176:179], v[20:23]
	v_mfma_f32_16x16x32_bf16 v[16:19], v[152:155], v[176:179], v[16:19]
	v_mfma_f32_16x16x32_bf16 v[4:7], v[144:147], v[184:187], v[4:7]
	v_mfma_f32_16x16x32_bf16 v[0:3], v[152:155], v[184:187], v[0:3]
	v_mfma_f32_16x16x32_bf16 v[52:55], v[148:151], v[164:167], v[52:55]
	v_mfma_f32_16x16x32_bf16 v[48:51], v[156:159], v[164:167], v[48:51]
	v_mfma_f32_16x16x32_bf16 v[36:39], v[148:151], v[172:175], v[36:39]
	v_mfma_f32_16x16x32_bf16 v[32:35], v[156:159], v[172:175], v[32:35]
	v_mfma_f32_16x16x32_bf16 v[20:23], v[148:151], v[180:183], v[20:23]
	v_mfma_f32_16x16x32_bf16 v[16:19], v[156:159], v[180:183], v[16:19]
	v_mfma_f32_16x16x32_bf16 v[4:7], v[148:151], v[188:191], v[4:7]
	v_mfma_f32_16x16x32_bf16 v[0:3], v[156:159], v[188:191], v[0:3]
	s_setprio 0
	s_barrier
	s_add_i32 s77, s77, 2
	s_add_u32 s46, s46, 0x100
	s_addc_u32 s47, s47, 0
	s_add_u32 s75, s75, 0x100
	s_addc_u32 s76, s76, 0
	s_cmpk_gt_u32 s77, 0x7d
	s_cbranch_scc0 .LBB0_815
